# forward-substitution L reads pipelined 7 deep with counted lgkmcnt; mixer_pre conv-input loads batched; dn_chain body rescheduled (conflict-free ds_read_b64, counted vmcnt, DN_OUT 16-wide)
# speedup vs baseline: 1.0161x; 1.0161x over previous
; #define LAS __attribute__((address_space(3)))
; __device__ __forceinline__ void mixer_pre_item(int item, const float* const* in, int l, unsigned char* ws, LAS unsigned char* lds, int tid, int lane, int wave) {
;     ...
;     __syncthreads();
; #pragma unroll
;     for (int i = 0; i < 9; ++i) { const int id = tid + 512 * i;
;         if (id < 35 * 128) { const int row = id >> 7, pc = id & 127, s = s0 - 3 + row;
;             u32x4v v = (u32x4v){0u, 0u, 0u, 0u};
;             if (s >= 0) v = *(const u32x4v*)(U + ((size_t)b * SEQ + s) * NIN + (pc < 32 ? pc * 8 : U_DQ + (pc - 32) * 8));
;             if (pc < 32) *(LAS u32x4v*)(STGL + row * 256 + pc * 8) = v; else *(LAS u32x4v*)(STGD + row * 768 + (pc - 32) * 8) = v; } }
;     __syncthreads();
.LBB0_567:
	v_mov_b32_e32 v34, v166
	s_ashr_i32 s18, s14, 6
	v_and_b32_e32 v2, 0x7f, v34
	v_lshlrev_b32_e32 v0, 3, v2
	v_or_b32_e32 v3, 0x400, v0
	v_cmp_gt_u32_e64 s[40:41], 32, v2
	s_lshl_b32 s9, s14, 5
	v_readlane_b32 s34, v251, 4
	v_cndmask_b32_e64 v0, v3, v0, s[40:41]
	s_and_b32 s30, s9, 0x7e0
	s_ashr_i32 s19, s18, 31
	v_lshlrev_b32_e32 v0, 1, v0
	v_readlane_b32 s35, v251, 5
	s_movk_i32 s31, 0x1180
	v_readfirstlane_b32 s15, v34
	s_lshl_b64 s[20:21], s[18:19], 11
	s_add_i32 s9, s30, -3
	v_cmp_lt_u32_e32 vcc, 31, v2
	v_lshl_add_u64 v[8:9], s[34:35], 0, v[0:1]
	v_lshl_add_u32 v6, v2, 4, 0
	v_cmp_gt_i32_e64 s[40:41], s31, v34
	s_barrier
	v_ashrrev_i32_e32 v7, 7, v34
	v_add_u32_e32 v0, s9, v7
	v_mov_b32_e32 v40, 0
	v_mov_b32_e32 v41, 0
	v_mov_b32_e32 v42, 0
	v_mov_b32_e32 v43, 0
	v_cmp_lt_i32_e64 s[40:41], -1, v0
	s_and_saveexec_b64 s[42:43], s[40:41]
	v_lshl_add_u64 v[2:3], s[20:21], 0, v[0:1]
	v_mad_u64_u32 v[4:5], s[34:35], v2, s36, v[8:9]
	v_mad_i32_i24 v5, v3, s36, v5
	global_load_dwordx4 v[40:43], v[4:5], off
	s_or_b64 exec, exec, s[42:43]
	v_add_u32_e32 v0, 4, v0
	v_lshl_add_u64 v[2:3], s[20:21], 0, v[0:1]
	v_mad_u64_u32 v[4:5], s[34:35], v2, s36, v[8:9]
	v_mad_i32_i24 v5, v3, s36, v5
	s_mov_b64 s[42:43], 0x5000
	global_load_dwordx4 v[44:47], v[4:5], off
	v_lshl_add_u64 v[4:5], v[4:5], 0, s[42:43]
	global_load_dwordx4 v[48:51], v[4:5], off
	v_lshl_add_u64 v[4:5], v[4:5], 0, s[42:43]
	global_load_dwordx4 v[52:55], v[4:5], off
	v_lshl_add_u64 v[4:5], v[4:5], 0, s[42:43]
	global_load_dwordx4 v[56:59], v[4:5], off
	v_lshl_add_u64 v[4:5], v[4:5], 0, s[42:43]
	global_load_dwordx4 v[60:63], v[4:5], off
	v_lshl_add_u64 v[4:5], v[4:5], 0, s[42:43]
	global_load_dwordx4 v[64:67], v[4:5], off
	v_lshl_add_u64 v[4:5], v[4:5], 0, s[42:43]
	global_load_dwordx4 v[68:71], v[4:5], off
	v_lshl_add_u64 v[4:5], v[4:5], 0, s[42:43]
	s_movk_i32 s31, 0x180
	v_cmp_gt_i32_e64 s[40:41], s31, v34
	s_and_saveexec_b64 s[38:39], s[40:41]
	global_load_dwordx4 v[72:75], v[4:5], off
	s_or_b64 exec, exec, s[38:39]
	v_lshl_add_u32 v10, v7, 9, v6
	s_movk_i32 s31, 0x600
	v_mad_u32_u24 v11, v7, s31, v6
	v_add_u32_e32 v11, 0x4400, v11
	v_mov_b32_e32 v2, 0x800
	v_mov_b32_e32 v3, 0x1800
	v_cndmask_b32_e32 v10, v10, v11, vcc
	v_cndmask_b32_e32 v11, v2, v3, vcc
	s_waitcnt vmcnt(7)
	ds_write_b128 v10, v[40:43]
	v_add_u32_e32 v10, v10, v11
	s_waitcnt vmcnt(6)
	ds_write_b128 v10, v[44:47]
	v_add_u32_e32 v10, v10, v11
	s_waitcnt vmcnt(5)
	ds_write_b128 v10, v[48:51]
	v_add_u32_e32 v10, v10, v11
	s_waitcnt vmcnt(4)
	ds_write_b128 v10, v[52:55]
	v_add_u32_e32 v10, v10, v11
	s_waitcnt vmcnt(3)
	ds_write_b128 v10, v[56:59]
	v_add_u32_e32 v10, v10, v11
	s_waitcnt vmcnt(2)
	ds_write_b128 v10, v[60:63]
	v_add_u32_e32 v10, v10, v11
	s_waitcnt vmcnt(1)
	ds_write_b128 v10, v[64:67]
	v_add_u32_e32 v10, v10, v11
	s_waitcnt vmcnt(0)
	ds_write_b128 v10, v[68:71]
	v_add_u32_e32 v10, v10, v11
	s_waitcnt vmcnt(0)
	s_and_saveexec_b64 s[38:39], s[40:41]
	ds_write_b128 v10, v[72:75]
	s_or_b64 exec, exec, s[38:39]
	s_bfe_u32 s9, s8, 0x60005
	s_ashr_i32 s31, s15, 6
	v_and_b32_e32 v35, 63, v34
	s_cmp_lt_i32 s31, 24
	s_waitcnt lgkmcnt(0)
	s_barrier
	s_cbranch_scc0 .LBB0_633
	v_lshlrev_b32_e32 v0, 1, v35
	v_readlane_b32 s33, v248, 48
	s_lshl_b32 s35, s9, 5
	s_lshl_b32 s34, s31, 5
	v_add_u32_e32 v18, s33, v0
	s_lshl_b32 s33, s31, 4
	v_readlane_b32 s38, v249, 59
	v_readlane_b32 s39, v249, 60
	s_add_u32 s35, s20, s35
	s_addc_u32 s42, s21, 0
	s_waitcnt vmcnt(0)
	v_lshl_add_u64 v[2:3], s[38:39], 0, v[0:1]
	s_branch .LBB0_615

; __device__ __forceinline__ unsigned short f2bf(float f) { return (unsigned short)(pg8::cvt_pk_bf16(f, 0.f) & 0xffffu); }
; __device__ __forceinline__ void convert_p(const float* p, bf16_t* pbf, size_t gtid, size_t gthreads) {
;     asm volatile("" : "+v"(gtid));
;     const size_t n8 = (size_t)T * PLE / 8;
;     for (size_t i = gtid; i < n8; i += gthreads) { const f32x4 a = ((const f32x4*)p)[2 * i], b = ((const f32x4*)p)[2 * i + 1];
; __device__ __forceinline__ void mixer_pre_item(int item, const float* const* in, int l, unsigned char* ws, LAS unsigned char* lds, int tid, int lane, int wave) {
;     ...
;     if (tid < 256) {
;         float h = 0.f, P = 1.f;
;         bf16_t* LH = (bf16_t*)(ws + WS_R2 + R2_LH) + g0 * 256 + tid; bf16_t* PC = (bf16_t*)(ws + WS_R2 + R2_PC) + g0 * 256 + tid;
; #pragma unroll 8
;         for (int t = 0; t < 32; ++t) { const float a = AF[t * 256 + tid], uu = XRF[t * 256 + tid]; h = a * h + uu; P *= a; LH[t * 256] = f2bf(h); PC[t * 256] = f2bf(P); }
;         float2 ag; ag.x = P; ag.y = h; ((float2*)(ws + WS_R2 + R2_AGG))[(size_t)(b * 64 + c) * 256 + tid] = ag;
.LBB0_723:
	ds_read2st64_b32 v[8:9], v0 offset1:128
	s_waitcnt lgkmcnt(0)
	v_fmac_f32_e32 v8, v4, v9
	v_lshl_add_u64 v[4:5], v[2:3], 0, s[18:19]
	v_add_co_u32_e32 v10, vcc, 0x14900000, v4
	v_cvt_pk_bf16_f32 v7, v8, v1
	v_mul_f32_e32 v6, v6, v9
	s_nop 0
	v_addc_co_u32_e32 v11, vcc, 0, v5, vcc
	v_add_co_u32_e32 v12, vcc, 0x15900000, v4
	global_store_short v[10:11], v7, off
	v_cvt_pk_bf16_f32 v7, v6, v1
	s_nop 0
	v_addc_co_u32_e32 v13, vcc, 0, v5, vcc
	ds_read2st64_b32 v[4:5], v0 offset0:4 offset1:132
	global_store_short v[12:13], v7, off
	s_add_u32 s18, s18, 0x1000
	s_addc_u32 s19, s19, 0
	s_cmpk_eq_i32 s18, 0x4000
	s_waitcnt lgkmcnt(0)
	v_mul_f32_e32 v9, v6, v5
	v_fmac_f32_e32 v4, v8, v5
	v_cvt_pk_bf16_f32 v5, v4, v1
	global_store_short v[10:11], v5, off offset:512
	v_cvt_pk_bf16_f32 v5, v9, v1
	ds_read2st64_b32 v[6:7], v0 offset0:8 offset1:136
	global_store_short v[12:13], v5, off offset:512
	s_waitcnt lgkmcnt(0)
	v_fmac_f32_e32 v6, v4, v7
	v_cvt_pk_bf16_f32 v4, v6, v1
	v_mul_f32_e32 v8, v9, v7
	global_store_short v[10:11], v4, off offset:1024
	v_cvt_pk_bf16_f32 v4, v8, v1
	global_store_short v[12:13], v4, off offset:1024
	ds_read2st64_b32 v[4:5], v0 offset0:12 offset1:140
	s_waitcnt lgkmcnt(0)
	v_mul_f32_e32 v8, v8, v5
	v_fmac_f32_e32 v4, v6, v5
	v_cvt_pk_bf16_f32 v5, v4, v1
	global_store_short v[10:11], v5, off offset:1536
	v_cvt_pk_bf16_f32 v5, v8, v1
	ds_read2st64_b32 v[6:7], v0 offset0:16 offset1:144
	global_store_short v[12:13], v5, off offset:1536
	s_waitcnt lgkmcnt(0)
	v_fmac_f32_e32 v6, v4, v7
	v_cvt_pk_bf16_f32 v4, v6, v1
	v_mul_f32_e32 v8, v8, v7
	global_store_short v[10:11], v4, off offset:2048
	v_cvt_pk_bf16_f32 v4, v8, v1
	global_store_short v[12:13], v4, off offset:2048
	ds_read2st64_b32 v[4:5], v0 offset0:20 offset1:148
	s_waitcnt lgkmcnt(0)
	v_mul_f32_e32 v7, v8, v5
	v_fmac_f32_e32 v4, v6, v5
	v_cvt_pk_bf16_f32 v5, v4, v1
	global_store_short v[10:11], v5, off offset:2560
	v_cvt_pk_bf16_f32 v5, v7, v1
	ds_read2st64_b32 v[8:9], v0 offset0:24 offset1:152
	global_store_short v[12:13], v5, off offset:2560
	s_waitcnt lgkmcnt(0)
	v_fmac_f32_e32 v8, v4, v9
	v_cvt_pk_bf16_f32 v4, v8, v1
	v_mul_f32_e32 v6, v7, v9
	global_store_short v[10:11], v4, off offset:3072
	v_cvt_pk_bf16_f32 v4, v6, v1
	global_store_short v[12:13], v4, off offset:3072
	ds_read2st64_b32 v[4:5], v0 offset0:28 offset1:156
	v_add_u32_e32 v0, 0x2000, v0
	s_waitcnt lgkmcnt(0)
	v_mul_f32_e32 v6, v6, v5
	v_fmac_f32_e32 v4, v8, v5
	v_cvt_pk_bf16_f32 v5, v4, v1
	global_store_short v[10:11], v5, off offset:3584
	v_cvt_pk_bf16_f32 v5, v6, v1
	global_store_short v[12:13], v5, off offset:3584
	s_cbranch_scc0 .LBB0_723
	s_ashr_i32 s15, s14, 31
	s_lshl_b64 s[18:19], s[14:15], 11
	v_readlane_b32 s9, v249, 3
	s_add_u32 s18, s9, s18
	v_readlane_b32 s9, v249, 4
	s_addc_u32 s19, s9, s19
	v_lshl_add_u64 v[2:3], v[34:35], 3, s[18:19]
	v_mov_b32_e32 v7, v4
	global_store_dwordx2 v[2:3], v[6:7], off
	s_branch .LBB0_566
.LBB0_743:
	v_mov_b32_e32 v2, v158
	v_readlane_b32 s0, v249, 5
	v_readlane_b32 s1, v249, 6
	v_ashrrev_i32_e32 v3, 31, v2
	s_nop 0
	v_lshl_add_u64 v[2:3], s[0:1], 0, v[2:3]
	s_mov_b64 s[0:1], 0x100000
	s_nop 0
	v_cmp_gt_u64_e32 vcc, s[0:1], v[2:3]
	s_and_saveexec_b64 s[10:11], vcc
	v_readlane_b32 s8, v249, 7
	v_readlane_b32 s9, v249, 8
	s_cbranch_execz .LBB0_746
	v_readlane_b32 s6, v251, 6
	v_readlane_b32 s7, v251, 7
	s_lshl_b64 s[0:1], s[90:91], 25
	v_lshlrev_b64 v[6:7], 5, v[2:3]
	v_lshl_add_u64 v[4:5], v[2:3], 4, s[6:7]
	v_readlane_b32 s6, v248, 2
	s_add_u32 s0, s6, s0
	v_readlane_b32 s6, v248, 3
	s_addc_u32 s1, s6, s1
	v_lshl_add_u64 v[6:7], s[0:1], 0, v[6:7]
	s_mov_b64 s[12:13], 0

; #define LAS __attribute__((address_space(3)))
; __device__ __forceinline__ void dn_prep_item(int item, unsigned char* ws, LAS unsigned char* lds, int tid, int lane, int wave) {
;     ...
;         const LAS float* Lh = LM + hd * 4096;
; #pragma unroll
;         for (int i = 1; i < 64; ++i) {
;             float acc = x[i];
; #pragma unroll
;             for (int j4 = 0; j4 < (i + 3) / 4; ++j4) { const f32x4 lv = *(const LAS f32x4*)(Lh + i * 64 + 4 * j4);
; #pragma unroll
;                 for (int jj = 0; jj < 4; ++jj) if (4 * j4 + jj < i) acc -= lv[jj] * x[4 * j4 + jj]; }
;             x[i] = acc;
;         }
.LBB0_826:
	s_lshl_b32 s0, s10, 14
	s_add_i32 s0, s0, 0
	v_mov_b32_e32 v57, s0
	ds_read_b128 v[168:171], v57 offset:256
	ds_read_b128 v[172:175], v57 offset:512
	ds_read_b128 v[176:179], v57 offset:768
	ds_read_b128 v[180:183], v57 offset:1024
	ds_read_b128 v[184:187], v57 offset:1280
	ds_read_b128 v[188:191], v57 offset:1296
	ds_read_b128 v[192:195], v57 offset:1536
	s_mov_b64 s[10:11], -1
	s_andn2_b64 vcc, exec, s[12:13]
	s_waitcnt lgkmcnt(6)
	v_fma_f32 v26, -v127, v168, v129
	ds_read_b128 v[196:199], v57 offset:1552
	s_waitcnt lgkmcnt(6)
	v_fma_f32 v27, -v127, v172, v36
	v_fma_f32 v27, -v173, v26, v27
	ds_read_b128 v[200:203], v57 offset:1792
	s_waitcnt lgkmcnt(6)
	v_fma_f32 v30, -v127, v176, v37
	ds_read_b128 v[204:207], v57 offset:1808
	v_fma_f32 v30, -v177, v26, v30
	v_fma_f32 v30, -v178, v27, v30
	s_waitcnt lgkmcnt(6)
	v_fma_f32 v31, -v127, v180, v42
	v_fma_f32 v31, -v26, v181, v31
	v_fma_f32 v31, -v182, v27, v31
	v_fma_f32 v31, -v183, v30, v31
	ds_read_b128 v[168:171], v57 offset:2048
	s_waitcnt lgkmcnt(6)
	v_fma_f32 v32, -v127, v184, v43
	v_fma_f32 v32, -v26, v185, v32
	v_fma_f32 v32, -v186, v27, v32
	v_fma_f32 v32, -v187, v30, v32
	ds_read_b128 v[172:175], v57 offset:2064
	s_waitcnt lgkmcnt(6)
	v_fma_f32 v32, -v188, v31, v32
	ds_read_b128 v[176:179], v57 offset:2304
	s_waitcnt lgkmcnt(6)
	v_fma_f32 v33, -v127, v192, v50
	v_fma_f32 v33, -v26, v193, v33
	v_fma_f32 v33, -v27, v194, v33
	v_fma_f32 v33, -v195, v30, v33
	ds_read_b128 v[180:183], v57 offset:2320
	s_waitcnt lgkmcnt(6)
	v_fma_f32 v33, -v196, v31, v33
	v_fma_f32 v33, -v197, v32, v33
	ds_read_b128 v[184:187], v57 offset:2336
	s_waitcnt lgkmcnt(6)
	v_fma_f32 v36, -v127, v200, v51
	v_fma_f32 v36, -v26, v201, v36
	v_fma_f32 v36, -v27, v202, v36
	v_fma_f32 v40, -v30, v203, v36
	ds_read_b128 v[188:191], v57 offset:2560
	s_waitcnt lgkmcnt(6)
	v_fma_f32 v36, -v31, v204, v40
	v_fma_f32 v36, -v205, v32, v36
	v_fma_f32 v36, -v206, v33, v36
	ds_read_b128 v[192:195], v57 offset:2576
	s_waitcnt lgkmcnt(6)
	v_fma_f32 v37, -v127, v168, v52
	v_fma_f32 v37, -v26, v169, v37
	v_fma_f32 v37, -v27, v170, v37
	v_fma_f32 v37, -v30, v171, v37
	ds_read_b128 v[196:199], v57 offset:2592
	s_waitcnt lgkmcnt(6)
	v_fma_f32 v37, -v31, v172, v37
	v_fma_f32 v37, -v32, v173, v37
	v_fma_f32 v37, -v174, v33, v37
	v_fma_f32 v37, -v175, v36, v37
	ds_read_b128 v[200:203], v57 offset:2816
	s_waitcnt lgkmcnt(6)
	v_fma_f32 v38, -v127, v176, v53
	v_fma_f32 v38, -v26, v177, v38
	v_fma_f32 v38, -v27, v178, v38
	v_fma_f32 v42, -v30, v179, v38
	ds_read_b128 v[204:207], v57 offset:2832
	s_waitcnt lgkmcnt(6)
	v_fma_f32 v38, -v31, v180, v42
	v_fma_f32 v38, -v32, v181, v38
	v_fma_f32 v38, -v182, v33, v38
	v_fma_f32 v42, -v183, v36, v38
	ds_read_b128 v[168:171], v57 offset:2848
	s_waitcnt lgkmcnt(6)
	v_fma_f32 v38, -v184, v37, v42
	ds_read_b128 v[172:175], v57 offset:3072
	s_waitcnt lgkmcnt(6)
	v_fma_f32 v39, -v127, v188, v70
	v_fma_f32 v39, -v26, v189, v39
	v_fma_f32 v39, -v27, v190, v39
	v_fma_f32 v39, -v30, v191, v39
	ds_read_b128 v[176:179], v57 offset:3088
	s_waitcnt lgkmcnt(6)
	v_fma_f32 v39, -v31, v192, v39
	v_fma_f32 v39, -v32, v193, v39
	v_fma_f32 v39, -v33, v194, v39
	v_fma_f32 v39, -v195, v36, v39
	ds_read_b128 v[180:183], v57 offset:3104
	s_waitcnt lgkmcnt(6)
	v_fma_f32 v39, -v196, v37, v39
	v_fma_f32 v39, -v197, v38, v39
	ds_read_b128 v[184:187], v57 offset:3328
	s_waitcnt lgkmcnt(6)
	v_fma_f32 v40, -v127, v200, v71
	v_fma_f32 v40, -v26, v201, v40
	v_fma_f32 v40, -v27, v202, v40
	v_fma_f32 v44, -v30, v203, v40
	ds_read_b128 v[188:191], v57 offset:3344
	s_waitcnt lgkmcnt(6)
	v_fma_f32 v40, -v31, v204, v44
	v_fma_f32 v40, -v32, v205, v40
	v_fma_f32 v40, -v33, v206, v40
	v_fma_f32 v44, -v36, v207, v40
	ds_read_b128 v[192:195], v57 offset:3360
	s_waitcnt lgkmcnt(6)
	v_fma_f32 v40, -v37, v168, v44
	v_fma_f32 v40, -v169, v38, v40
	v_fma_f32 v40, -v170, v39, v40
	ds_read_b128 v[196:199], v57 offset:3376
	s_waitcnt lgkmcnt(6)
	v_fma_f32 v41, -v127, v172, v68
	v_fma_f32 v41, -v26, v173, v41
	v_fma_f32 v41, -v27, v174, v41
	v_fma_f32 v41, -v30, v175, v41
	ds_read_b128 v[200:203], v57 offset:3584
	s_waitcnt lgkmcnt(6)
	v_fma_f32 v41, -v31, v176, v41
	v_fma_f32 v41, -v32, v177, v41
	v_fma_f32 v41, -v33, v178, v41
	v_fma_f32 v41, -v36, v179, v41
	ds_read_b128 v[204:207], v57 offset:3600
	s_waitcnt lgkmcnt(6)
	v_fma_f32 v41, -v37, v180, v41
	v_fma_f32 v41, -v38, v181, v41
	v_fma_f32 v41, -v182, v39, v41
	v_fma_f32 v41, -v183, v40, v41
	ds_read_b128 v[168:171], v57 offset:3616
	s_waitcnt lgkmcnt(6)
	v_fma_f32 v42, -v127, v184, v69
	v_fma_f32 v42, -v26, v185, v42
	v_fma_f32 v42, -v27, v186, v42
	v_fma_f32 v46, -v30, v187, v42
	ds_read_b128 v[172:175], v57 offset:3632
	s_waitcnt lgkmcnt(6)
	v_fma_f32 v42, -v31, v188, v46
	v_fma_f32 v42, -v32, v189, v42
	v_fma_f32 v42, -v33, v190, v42
	v_fma_f32 v46, -v36, v191, v42
	ds_read_b128 v[176:179], v57 offset:3840
	s_waitcnt lgkmcnt(6)
	v_fma_f32 v42, -v37, v192, v46
	v_fma_f32 v42, -v38, v193, v42
	v_fma_f32 v42, -v194, v39, v42
	v_fma_f32 v46, -v195, v40, v42
	ds_read_b128 v[180:183], v57 offset:3856
	s_waitcnt lgkmcnt(6)
	v_fma_f32 v42, -v196, v41, v46
	ds_read_b128 v[184:187], v57 offset:3872
	s_waitcnt lgkmcnt(6)
	v_fma_f32 v43, -v127, v200, v74
	v_fma_f32 v43, -v26, v201, v43
	v_fma_f32 v43, -v27, v202, v43
	v_fma_f32 v43, -v30, v203, v43
	ds_read_b128 v[188:191], v57 offset:3888
	s_waitcnt lgkmcnt(6)
	v_fma_f32 v43, -v31, v204, v43
	v_fma_f32 v43, -v32, v205, v43
	v_fma_f32 v43, -v33, v206, v43
	v_fma_f32 v43, -v36, v207, v43
	ds_read_b128 v[192:195], v57 offset:4096
	s_waitcnt lgkmcnt(6)
; #define LAS __attribute__((address_space(3)))
; __device__ __forceinline__ void dn_prep_item(int item, unsigned char* ws, LAS unsigned char* lds, int tid, int lane, int wave) {
;     ...
; #pragma unroll
;         for (int i = 1; i < 64; ++i) {
;             float acc = x[i];
; #pragma unroll
;             for (int j4 = 0; j4 < (i + 3) / 4; ++j4) { const f32x4 lv = *(const LAS f32x4*)(Lh + i * 64 + 4 * j4);
; #pragma unroll
;                 for (int jj = 0; jj < 4; ++jj) if (4 * j4 + jj < i) acc -= lv[jj] * x[4 * j4 + jj]; }
;             x[i] = acc;
;         }
	v_fma_f32 v43, -v37, v168, v43
	v_fma_f32 v43, -v38, v169, v43
	v_fma_f32 v43, -v39, v170, v43
	v_fma_f32 v43, -v171, v40, v43
	ds_read_b128 v[196:199], v57 offset:4112
	s_waitcnt lgkmcnt(6)
	v_fma_f32 v43, -v172, v41, v43
	v_fma_f32 v43, -v173, v42, v43
	ds_read_b128 v[200:203], v57 offset:4128
	s_waitcnt lgkmcnt(6)
	v_fma_f32 v44, -v127, v176, v75
	v_fma_f32 v44, -v26, v177, v44
	v_fma_f32 v44, -v27, v178, v44
	v_fma_f32 v50, -v30, v179, v44
	ds_read_b128 v[204:207], v57 offset:4144
	s_waitcnt lgkmcnt(6)
	v_fma_f32 v44, -v31, v180, v50
	v_fma_f32 v44, -v32, v181, v44
	v_fma_f32 v44, -v33, v182, v44
	v_fma_f32 v50, -v36, v183, v44
	ds_read_b128 v[168:171], v57 offset:4352
	s_waitcnt lgkmcnt(6)
	v_fma_f32 v44, -v37, v184, v50
	v_fma_f32 v44, -v38, v185, v44
	v_fma_f32 v44, -v39, v186, v44
	v_fma_f32 v50, -v40, v187, v44
	ds_read_b128 v[172:175], v57 offset:4368
	s_waitcnt lgkmcnt(6)
	v_fma_f32 v44, -v41, v188, v50
	ds_read_b128 v[176:179], v57 offset:4384
	v_fma_f32 v44, -v189, v42, v44
	v_fma_f32 v44, -v190, v43, v44
	s_waitcnt lgkmcnt(6)
	v_fma_f32 v45, -v127, v192, v72
	v_fma_f32 v45, -v26, v193, v45
	v_fma_f32 v45, -v27, v194, v45
	v_fma_f32 v45, -v30, v195, v45
	ds_read_b128 v[180:183], v57 offset:4400
	s_waitcnt lgkmcnt(6)
	v_fma_f32 v45, -v31, v196, v45
	v_fma_f32 v45, -v32, v197, v45
	v_fma_f32 v45, -v33, v198, v45
	v_fma_f32 v45, -v36, v199, v45
	ds_read_b128 v[184:187], v57 offset:4416
	s_waitcnt lgkmcnt(6)
	v_fma_f32 v45, -v37, v200, v45
	v_fma_f32 v45, -v38, v201, v45
	v_fma_f32 v45, -v39, v202, v45
	v_fma_f32 v45, -v40, v203, v45
	ds_read_b128 v[188:191], v57 offset:4608
	s_waitcnt lgkmcnt(6)
	v_fma_f32 v45, -v41, v204, v45
	v_fma_f32 v45, -v42, v205, v45
	v_fma_f32 v45, -v206, v43, v45
	v_fma_f32 v45, -v207, v44, v45
	ds_read_b128 v[192:195], v57 offset:4624
	s_waitcnt lgkmcnt(6)
	v_fma_f32 v46, -v127, v168, v73
	v_fma_f32 v46, -v26, v169, v46
	v_fma_f32 v46, -v27, v170, v46
	v_fma_f32 v46, -v30, v171, v46
	ds_read_b128 v[196:199], v57 offset:4640
	s_waitcnt lgkmcnt(6)
	v_fma_f32 v46, -v31, v172, v46
	v_fma_f32 v46, -v32, v173, v46
	v_fma_f32 v46, -v33, v174, v46
	v_fma_f32 v46, -v36, v175, v46
	ds_read_b128 v[200:203], v57 offset:4656
	s_waitcnt lgkmcnt(6)
	v_fma_f32 v46, -v37, v176, v46
	v_fma_f32 v46, -v38, v177, v46
	v_fma_f32 v46, -v39, v178, v46
	v_fma_f32 v46, -v40, v179, v46
	ds_read_b128 v[204:207], v57 offset:4672
	s_waitcnt lgkmcnt(6)
	v_fma_f32 v46, -v41, v180, v46
	v_fma_f32 v46, -v42, v181, v46
	v_fma_f32 v46, -v182, v43, v46
	v_fma_f32 v46, -v183, v44, v46
	ds_read_b128 v[168:171], v57 offset:4864
	s_waitcnt lgkmcnt(6)
	v_fma_f32 v46, -v184, v45, v46
	ds_read_b128 v[172:175], v57 offset:4880
	s_waitcnt lgkmcnt(6)
	v_fma_f32 v47, -v127, v188, v60
	v_fma_f32 v47, -v26, v189, v47
	v_fma_f32 v47, -v27, v190, v47
	v_fma_f32 v47, -v30, v191, v47
	ds_read_b128 v[176:179], v57 offset:5120
	s_waitcnt lgkmcnt(6)
	v_fma_f32 v47, -v31, v192, v47
	v_fma_f32 v47, -v32, v193, v47
	v_fma_f32 v47, -v33, v194, v47
	v_fma_f32 v47, -v36, v195, v47
	ds_read_b128 v[180:183], v57 offset:4896
	s_waitcnt lgkmcnt(6)
	v_fma_f32 v47, -v37, v196, v47
	v_fma_f32 v47, -v38, v197, v47
	v_fma_f32 v47, -v39, v198, v47
	v_fma_f32 v47, -v40, v199, v47
	ds_read_b128 v[184:187], v57 offset:4912
	s_waitcnt lgkmcnt(6)
	v_fma_f32 v47, -v41, v200, v47
	v_fma_f32 v47, -v42, v201, v47
	v_fma_f32 v47, -v43, v202, v47
	v_fma_f32 v47, -v203, v44, v47
	ds_read_b128 v[188:191], v57 offset:4928
	s_waitcnt lgkmcnt(6)
	v_fma_f32 v47, -v204, v45, v47
	v_fma_f32 v47, -v205, v46, v47
	ds_read_b128 v[192:195], v57 offset:5136
	s_waitcnt lgkmcnt(6)
	v_fma_f32 v50, -v127, v168, v61
	v_fma_f32 v50, -v26, v169, v50
	v_fma_f32 v50, -v27, v170, v50
	v_fma_f32 v56, -v30, v171, v50
	ds_read_b128 v[196:199], v57 offset:5152
	ds_read_b128 v[200:203], v57 offset:5168
	s_waitcnt lgkmcnt(7)
	v_fma_f32 v50, -v31, v172, v56
	v_fma_f32 v50, -v32, v173, v50
	v_fma_f32 v50, -v33, v174, v50
	v_fma_f32 v56, -v36, v175, v50
	ds_read_b128 v[204:207], v57 offset:5184
	s_waitcnt lgkmcnt(6)
	v_fma_f32 v50, -v37, v180, v56
	v_fma_f32 v50, -v38, v181, v50
	v_fma_f32 v50, -v39, v182, v50
	v_fma_f32 v56, -v40, v183, v50
	ds_read_b128 v[168:171], v57 offset:5376
	s_waitcnt lgkmcnt(6)
	v_fma_f32 v50, -v41, v184, v56
	v_fma_f32 v50, -v42, v185, v50
	v_fma_f32 v50, -v43, v186, v50
	v_fma_f32 v56, -v44, v187, v50
	ds_read_b128 v[172:175], v57 offset:5392
	s_waitcnt lgkmcnt(6)
	v_fma_f32 v50, -v45, v188, v56
	v_fma_f32 v50, -v189, v46, v50
	v_fma_f32 v51, -v127, v176, v96
	v_fma_f32 v51, -v26, v177, v51
	v_fma_f32 v51, -v27, v178, v51
	v_fma_f32 v51, -v30, v179, v51
	ds_read_b128 v[176:179], v57 offset:5408
	v_fma_f32 v50, -v190, v47, v50
	s_waitcnt lgkmcnt(6)
	v_fma_f32 v51, -v31, v192, v51
	v_fma_f32 v51, -v32, v193, v51
	v_fma_f32 v51, -v33, v194, v51
	v_fma_f32 v51, -v36, v195, v51
	ds_read_b128 v[180:183], v57 offset:5424
	s_waitcnt lgkmcnt(6)
	v_fma_f32 v51, -v37, v196, v51
	v_fma_f32 v51, -v38, v197, v51
	v_fma_f32 v51, -v39, v198, v51
	v_fma_f32 v51, -v40, v199, v51
	ds_read_b128 v[184:187], v57 offset:5440
	s_waitcnt lgkmcnt(6)
	v_fma_f32 v51, -v41, v200, v51
	v_fma_f32 v51, -v42, v201, v51
	v_fma_f32 v51, -v43, v202, v51
	v_fma_f32 v51, -v44, v203, v51
	ds_read_b128 v[188:191], v57 offset:5456
	s_waitcnt lgkmcnt(6)
	v_fma_f32 v51, -v45, v204, v51
	v_fma_f32 v51, -v46, v205, v51
	v_fma_f32 v51, -v206, v47, v51
	v_fma_f32 v51, -v207, v50, v51
	ds_read_b128 v[192:195], v57 offset:5632
	s_waitcnt lgkmcnt(6)
	v_fma_f32 v52, -v127, v168, v97
	v_fma_f32 v52, -v26, v169, v52
	v_fma_f32 v52, -v27, v170, v52
	v_fma_f32 v52, -v30, v171, v52
	ds_read_b128 v[196:199], v57 offset:5648
	s_waitcnt lgkmcnt(6)
; #define LAS __attribute__((address_space(3)))
; __device__ __forceinline__ void dn_prep_item(int item, unsigned char* ws, LAS unsigned char* lds, int tid, int lane, int wave) {
;     ...
; #pragma unroll
;         for (int i = 1; i < 64; ++i) {
;             float acc = x[i];
; #pragma unroll
;             for (int j4 = 0; j4 < (i + 3) / 4; ++j4) { const f32x4 lv = *(const LAS f32x4*)(Lh + i * 64 + 4 * j4);
; #pragma unroll
;                 for (int jj = 0; jj < 4; ++jj) if (4 * j4 + jj < i) acc -= lv[jj] * x[4 * j4 + jj]; }
;             x[i] = acc;
;         }
	v_fma_f32 v52, -v31, v172, v52
	v_fma_f32 v52, -v32, v173, v52
	v_fma_f32 v52, -v33, v174, v52
	v_fma_f32 v52, -v36, v175, v52
	ds_read_b128 v[200:203], v57 offset:5664
	s_waitcnt lgkmcnt(6)
	v_fma_f32 v52, -v37, v176, v52
	v_fma_f32 v52, -v38, v177, v52
	v_fma_f32 v52, -v39, v178, v52
	v_fma_f32 v52, -v40, v179, v52
	ds_read_b128 v[204:207], v57 offset:5680
	s_waitcnt lgkmcnt(6)
	v_fma_f32 v52, -v41, v180, v52
	v_fma_f32 v52, -v42, v181, v52
	v_fma_f32 v52, -v43, v182, v52
	v_fma_f32 v52, -v44, v183, v52
	ds_read_b128 v[168:171], v57 offset:5696
	s_waitcnt lgkmcnt(6)
	v_fma_f32 v52, -v45, v184, v52
	v_fma_f32 v52, -v46, v185, v52
	v_fma_f32 v52, -v186, v47, v52
	v_fma_f32 v52, -v187, v50, v52
	ds_read_b128 v[172:175], v57 offset:5712
	s_waitcnt lgkmcnt(6)
	v_fma_f32 v52, -v188, v51, v52
	ds_read_b128 v[176:179], v57 offset:5888
	s_waitcnt lgkmcnt(6)
	v_fma_f32 v53, -v127, v192, v88
	v_fma_f32 v53, -v26, v193, v53
	v_fma_f32 v53, -v27, v194, v53
	v_fma_f32 v53, -v30, v195, v53
	ds_read_b128 v[180:183], v57 offset:5904
	s_waitcnt lgkmcnt(6)
	v_fma_f32 v53, -v31, v196, v53
	v_fma_f32 v53, -v32, v197, v53
	v_fma_f32 v53, -v33, v198, v53
	v_fma_f32 v53, -v36, v199, v53
	ds_read_b128 v[184:187], v57 offset:5920
	s_waitcnt lgkmcnt(6)
	v_fma_f32 v53, -v37, v200, v53
	v_fma_f32 v53, -v38, v201, v53
	v_fma_f32 v53, -v39, v202, v53
	v_fma_f32 v53, -v40, v203, v53
	ds_read_b128 v[188:191], v57 offset:5936
	s_waitcnt lgkmcnt(6)
	v_fma_f32 v53, -v41, v204, v53
	v_fma_f32 v53, -v42, v205, v53
	v_fma_f32 v53, -v43, v206, v53
	v_fma_f32 v53, -v44, v207, v53
	ds_read_b128 v[192:195], v57 offset:5952
	s_waitcnt lgkmcnt(6)
	v_fma_f32 v53, -v45, v168, v53
	v_fma_f32 v53, -v46, v169, v53
	v_fma_f32 v53, -v47, v170, v53
	v_fma_f32 v53, -v171, v50, v53
	ds_read_b128 v[196:199], v57 offset:5968
	s_waitcnt lgkmcnt(6)
	v_fma_f32 v53, -v172, v51, v53
	v_fma_f32 v53, -v173, v52, v53
	ds_read_b128 v[200:203], v57 offset:6144
	s_waitcnt lgkmcnt(6)
	v_fma_f32 v56, -v127, v176, v89
	v_fma_f32 v56, -v26, v177, v56
	v_fma_f32 v56, -v27, v178, v56
	v_fma_f32 v56, -v30, v179, v56
	ds_read_b128 v[204:207], v57 offset:6160
	s_waitcnt lgkmcnt(6)
	v_fma_f32 v56, -v31, v180, v56
	v_fma_f32 v56, -v32, v181, v56
	v_fma_f32 v56, -v33, v182, v56
	v_fma_f32 v56, -v36, v183, v56
	ds_read_b128 v[168:171], v57 offset:6176
	s_waitcnt lgkmcnt(6)
	v_fma_f32 v56, -v37, v184, v56
	v_fma_f32 v56, -v38, v185, v56
	v_fma_f32 v56, -v39, v186, v56
	v_fma_f32 v56, -v40, v187, v56
	ds_read_b128 v[172:175], v57 offset:6192
	s_waitcnt lgkmcnt(6)
	v_fma_f32 v56, -v41, v188, v56
	v_fma_f32 v56, -v42, v189, v56
	v_fma_f32 v56, -v43, v190, v56
	v_fma_f32 v56, -v44, v191, v56
	ds_read_b128 v[176:179], v57 offset:6208
	s_waitcnt lgkmcnt(6)
	v_fma_f32 v56, -v45, v192, v56
	v_fma_f32 v56, -v46, v193, v56
	v_fma_f32 v56, -v47, v194, v56
	v_fma_f32 v56, -v50, v195, v56
	ds_read_b128 v[180:183], v57 offset:6224
	s_waitcnt lgkmcnt(6)
	v_fma_f32 v56, -v51, v196, v56
	v_fma_f32 v56, -v197, v52, v56
	v_fma_f32 v56, -v198, v53, v56
	ds_read_b128 v[184:187], v57 offset:6400
	s_waitcnt lgkmcnt(6)
	v_fma_f32 v58, -v127, v200, v82
	v_fma_f32 v58, -v26, v201, v58
	v_fma_f32 v58, -v27, v202, v58
	v_fma_f32 v62, -v30, v203, v58
	ds_read_b128 v[188:191], v57 offset:6416
	s_waitcnt lgkmcnt(6)
	v_fma_f32 v58, -v31, v204, v62
	v_fma_f32 v58, -v32, v205, v58
	v_fma_f32 v58, -v33, v206, v58
	v_fma_f32 v62, -v36, v207, v58
	ds_read_b128 v[192:195], v57 offset:6432
	s_waitcnt lgkmcnt(6)
	v_fma_f32 v58, -v37, v168, v62
	v_fma_f32 v58, -v38, v169, v58
	v_fma_f32 v58, -v39, v170, v58
	v_fma_f32 v62, -v40, v171, v58
	ds_read_b128 v[196:199], v57 offset:6448
	s_waitcnt lgkmcnt(6)
	v_fma_f32 v58, -v41, v172, v62
	v_fma_f32 v58, -v42, v173, v58
	v_fma_f32 v58, -v43, v174, v58
	v_fma_f32 v62, -v44, v175, v58
	ds_read_b128 v[200:203], v57 offset:6464
	s_waitcnt lgkmcnt(6)
	v_fma_f32 v58, -v45, v176, v62
	v_fma_f32 v58, -v46, v177, v58
	v_fma_f32 v58, -v47, v178, v58
	v_fma_f32 v62, -v50, v179, v58
	ds_read_b128 v[204:207], v57 offset:6480
	s_waitcnt lgkmcnt(6)
	v_fma_f32 v58, -v51, v180, v62
	v_fma_f32 v58, -v52, v181, v58
	v_fma_f32 v58, -v182, v53, v58
	v_fma_f32 v58, -v183, v56, v58
	ds_read_b128 v[168:171], v57 offset:6496
	s_waitcnt lgkmcnt(6)
	v_fma_f32 v59, -v127, v184, v83
	v_fma_f32 v59, -v26, v185, v59
	v_fma_f32 v59, -v27, v186, v59
	v_fma_f32 v59, -v30, v187, v59
	ds_read_b128 v[172:175], v57 offset:6656
	s_waitcnt lgkmcnt(6)
	v_fma_f32 v59, -v31, v188, v59
	v_fma_f32 v59, -v32, v189, v59
	v_fma_f32 v59, -v33, v190, v59
	v_fma_f32 v59, -v36, v191, v59
	ds_read_b128 v[176:179], v57 offset:6672
	s_waitcnt lgkmcnt(6)
	v_fma_f32 v59, -v37, v192, v59
	v_fma_f32 v59, -v38, v193, v59
	v_fma_f32 v59, -v39, v194, v59
	v_fma_f32 v59, -v40, v195, v59
	ds_read_b128 v[180:183], v57 offset:6688
	s_waitcnt lgkmcnt(6)
	v_fma_f32 v59, -v41, v196, v59
	v_fma_f32 v59, -v42, v197, v59
	v_fma_f32 v59, -v43, v198, v59
	v_fma_f32 v59, -v44, v199, v59
	ds_read_b128 v[184:187], v57 offset:6704
	s_waitcnt lgkmcnt(6)
	v_fma_f32 v59, -v45, v200, v59
	v_fma_f32 v59, -v46, v201, v59
	v_fma_f32 v59, -v47, v202, v59
	v_fma_f32 v59, -v50, v203, v59
	ds_read_b128 v[188:191], v57 offset:6720
	s_waitcnt lgkmcnt(6)
	v_fma_f32 v59, -v51, v204, v59
	v_fma_f32 v59, -v52, v205, v59
	v_fma_f32 v59, -v206, v53, v59
	v_fma_f32 v59, -v207, v56, v59
	ds_read_b128 v[192:195], v57 offset:6736
	s_waitcnt lgkmcnt(6)
	v_fma_f32 v59, -v168, v58, v59
	ds_read_b128 v[196:199], v57 offset:6752
	s_waitcnt lgkmcnt(6)
	v_fma_f32 v60, -v127, v172, v66
	v_fma_f32 v60, -v26, v173, v60
	v_fma_f32 v60, -v27, v174, v60
	v_fma_f32 v64, -v30, v175, v60
	ds_read_b128 v[200:203], v57 offset:6912
	s_waitcnt lgkmcnt(6)
; #define LAS __attribute__((address_space(3)))
; __device__ __forceinline__ void dn_prep_item(int item, unsigned char* ws, LAS unsigned char* lds, int tid, int lane, int wave) {
;     ...
; #pragma unroll
;         for (int i = 1; i < 64; ++i) {
;             float acc = x[i];
; #pragma unroll
;             for (int j4 = 0; j4 < (i + 3) / 4; ++j4) { const f32x4 lv = *(const LAS f32x4*)(Lh + i * 64 + 4 * j4);
; #pragma unroll
;                 for (int jj = 0; jj < 4; ++jj) if (4 * j4 + jj < i) acc -= lv[jj] * x[4 * j4 + jj]; }
;             x[i] = acc;
;         }
	v_fma_f32 v60, -v31, v176, v64
	v_fma_f32 v60, -v32, v177, v60
	v_fma_f32 v60, -v33, v178, v60
	v_fma_f32 v64, -v36, v179, v60
	ds_read_b128 v[204:207], v57 offset:6928
	s_waitcnt lgkmcnt(6)
	v_fma_f32 v60, -v37, v180, v64
	v_fma_f32 v60, -v38, v181, v60
	v_fma_f32 v60, -v39, v182, v60
	v_fma_f32 v64, -v40, v183, v60
	ds_read_b128 v[168:171], v57 offset:6944
	s_waitcnt lgkmcnt(6)
	v_fma_f32 v60, -v41, v184, v64
	v_fma_f32 v60, -v42, v185, v60
	v_fma_f32 v60, -v43, v186, v60
	v_fma_f32 v64, -v44, v187, v60
	ds_read_b128 v[172:175], v57 offset:6960
	s_waitcnt lgkmcnt(6)
	v_fma_f32 v60, -v45, v188, v64
	v_fma_f32 v60, -v46, v189, v60
	v_fma_f32 v60, -v47, v190, v60
	v_fma_f32 v64, -v50, v191, v60
	ds_read_b128 v[176:179], v57 offset:6976
	s_waitcnt lgkmcnt(6)
	v_fma_f32 v60, -v51, v192, v64
	v_fma_f32 v60, -v52, v193, v60
	v_fma_f32 v60, -v53, v194, v60
	v_fma_f32 v64, -v195, v56, v60
	ds_read_b128 v[180:183], v57 offset:6992
	s_waitcnt lgkmcnt(6)
	v_fma_f32 v60, -v196, v58, v64
	ds_read_b128 v[184:187], v57 offset:7008
	v_fma_f32 v60, -v197, v59, v60
	s_waitcnt lgkmcnt(6)
	v_fma_f32 v61, -v127, v200, v67
	v_fma_f32 v61, -v26, v201, v61
	v_fma_f32 v61, -v27, v202, v61
	v_fma_f32 v61, -v30, v203, v61
	ds_read_b128 v[188:191], v57 offset:7168
	s_waitcnt lgkmcnt(6)
	v_fma_f32 v61, -v31, v204, v61
	v_fma_f32 v61, -v32, v205, v61
	v_fma_f32 v61, -v33, v206, v61
	v_fma_f32 v61, -v36, v207, v61
	ds_read_b128 v[192:195], v57 offset:7184
	s_waitcnt lgkmcnt(6)
	v_fma_f32 v61, -v37, v168, v61
	v_fma_f32 v61, -v38, v169, v61
	v_fma_f32 v61, -v39, v170, v61
	v_fma_f32 v61, -v40, v171, v61
	ds_read_b128 v[196:199], v57 offset:7200
	s_waitcnt lgkmcnt(6)
	v_fma_f32 v61, -v41, v172, v61
	v_fma_f32 v61, -v42, v173, v61
	v_fma_f32 v61, -v43, v174, v61
	v_fma_f32 v61, -v44, v175, v61
	ds_read_b128 v[200:203], v57 offset:7216
	s_waitcnt lgkmcnt(6)
	v_fma_f32 v61, -v45, v176, v61
	v_fma_f32 v61, -v46, v177, v61
	v_fma_f32 v61, -v47, v178, v61
	v_fma_f32 v61, -v50, v179, v61
	ds_read_b128 v[204:207], v57 offset:7232
	s_waitcnt lgkmcnt(6)
	v_fma_f32 v61, -v51, v180, v61
	v_fma_f32 v61, -v52, v181, v61
	v_fma_f32 v61, -v53, v182, v61
	v_fma_f32 v61, -v56, v183, v61
	ds_read_b128 v[168:171], v57 offset:7248
	s_waitcnt lgkmcnt(6)
	v_fma_f32 v61, -v58, v184, v61
	v_fma_f32 v61, -v185, v59, v61
	v_fma_f32 v61, -v186, v60, v61
	ds_read_b128 v[172:175], v57 offset:7264
	s_waitcnt lgkmcnt(6)
	v_fma_f32 v62, -v127, v188, v90
	v_fma_f32 v62, -v26, v189, v62
	v_fma_f32 v62, -v27, v190, v62
	v_fma_f32 v66, -v30, v191, v62
	ds_read_b128 v[176:179], v57 offset:7424
	s_waitcnt lgkmcnt(6)
	v_fma_f32 v62, -v31, v192, v66
	v_fma_f32 v62, -v32, v193, v62
	v_fma_f32 v62, -v33, v194, v62
	v_fma_f32 v66, -v36, v195, v62
	ds_read_b128 v[180:183], v57 offset:7440
	s_waitcnt lgkmcnt(6)
	v_fma_f32 v62, -v37, v196, v66
	v_fma_f32 v62, -v38, v197, v62
	v_fma_f32 v62, -v39, v198, v62
	v_fma_f32 v66, -v40, v199, v62
	ds_read_b128 v[184:187], v57 offset:7456
	s_waitcnt lgkmcnt(6)
	v_fma_f32 v62, -v41, v200, v66
	v_fma_f32 v62, -v42, v201, v62
	v_fma_f32 v62, -v43, v202, v62
	v_fma_f32 v66, -v44, v203, v62
	ds_read_b128 v[188:191], v57 offset:7472
	s_waitcnt lgkmcnt(6)
	v_fma_f32 v62, -v45, v204, v66
	v_fma_f32 v62, -v46, v205, v62
	v_fma_f32 v62, -v47, v206, v62
	v_fma_f32 v66, -v50, v207, v62
	ds_read_b128 v[192:195], v57 offset:7488
	s_waitcnt lgkmcnt(6)
	v_fma_f32 v62, -v51, v168, v66
	v_fma_f32 v62, -v52, v169, v62
	v_fma_f32 v62, -v53, v170, v62
	v_fma_f32 v66, -v56, v171, v62
	ds_read_b128 v[196:199], v57 offset:7504
	s_waitcnt lgkmcnt(6)
	v_fma_f32 v62, -v58, v172, v66
	v_fma_f32 v62, -v59, v173, v62
	v_fma_f32 v62, -v174, v60, v62
	v_fma_f32 v62, -v175, v61, v62
	ds_read_b128 v[200:203], v57 offset:7520
	s_waitcnt lgkmcnt(6)
	v_fma_f32 v63, -v127, v176, v91
	v_fma_f32 v63, -v26, v177, v63
	v_fma_f32 v63, -v27, v178, v63
	v_fma_f32 v63, -v30, v179, v63
	ds_read_b128 v[204:207], v57 offset:7536
	s_waitcnt lgkmcnt(6)
	v_fma_f32 v63, -v31, v180, v63
	v_fma_f32 v63, -v32, v181, v63
	v_fma_f32 v63, -v33, v182, v63
	v_fma_f32 v63, -v36, v183, v63
	ds_read_b128 v[168:171], v57 offset:7680
	s_waitcnt lgkmcnt(6)
	v_fma_f32 v63, -v37, v184, v63
	v_fma_f32 v63, -v38, v185, v63
	v_fma_f32 v63, -v39, v186, v63
	v_fma_f32 v63, -v40, v187, v63
	ds_read_b128 v[172:175], v57 offset:7696
	s_waitcnt lgkmcnt(6)
	v_fma_f32 v63, -v41, v188, v63
	v_fma_f32 v63, -v42, v189, v63
	v_fma_f32 v63, -v43, v190, v63
	v_fma_f32 v63, -v44, v191, v63
	ds_read_b128 v[176:179], v57 offset:7712
	s_waitcnt lgkmcnt(6)
	v_fma_f32 v63, -v45, v192, v63
	v_fma_f32 v63, -v46, v193, v63
	v_fma_f32 v63, -v47, v194, v63
	v_fma_f32 v63, -v50, v195, v63
	ds_read_b128 v[180:183], v57 offset:7728
	s_waitcnt lgkmcnt(6)
	v_fma_f32 v63, -v51, v196, v63
	v_fma_f32 v63, -v52, v197, v63
	v_fma_f32 v63, -v53, v198, v63
	v_fma_f32 v63, -v56, v199, v63
	ds_read_b128 v[184:187], v57 offset:7744
	s_waitcnt lgkmcnt(6)
	v_fma_f32 v63, -v58, v200, v63
	v_fma_f32 v63, -v59, v201, v63
	v_fma_f32 v63, -v202, v60, v63
	v_fma_f32 v63, -v203, v61, v63
	ds_read_b128 v[188:191], v57 offset:7760
	s_waitcnt lgkmcnt(6)
	v_fma_f32 v63, -v204, v62, v63
	ds_read_b128 v[192:195], v57 offset:7776
	s_waitcnt lgkmcnt(6)
	v_fma_f32 v64, -v127, v168, v80
	v_fma_f32 v64, -v26, v169, v64
	v_fma_f32 v64, -v27, v170, v64
	v_fma_f32 v68, -v30, v171, v64
	ds_read_b128 v[196:199], v57 offset:7792
	s_waitcnt lgkmcnt(6)
	v_fma_f32 v64, -v31, v172, v68
	v_fma_f32 v64, -v32, v173, v64
	v_fma_f32 v64, -v33, v174, v64
	v_fma_f32 v68, -v36, v175, v64
	ds_read_b128 v[200:203], v57 offset:7936
	s_waitcnt lgkmcnt(6)
; #define LAS __attribute__((address_space(3)))
; __device__ __forceinline__ void dn_prep_item(int item, unsigned char* ws, LAS unsigned char* lds, int tid, int lane, int wave) {
;     ...
; #pragma unroll
;         for (int i = 1; i < 64; ++i) {
;             float acc = x[i];
; #pragma unroll
;             for (int j4 = 0; j4 < (i + 3) / 4; ++j4) { const f32x4 lv = *(const LAS f32x4*)(Lh + i * 64 + 4 * j4);
; #pragma unroll
;                 for (int jj = 0; jj < 4; ++jj) if (4 * j4 + jj < i) acc -= lv[jj] * x[4 * j4 + jj]; }
;             x[i] = acc;
;         }
	v_fma_f32 v64, -v37, v176, v68
	v_fma_f32 v64, -v38, v177, v64
	v_fma_f32 v64, -v39, v178, v64
	v_fma_f32 v68, -v40, v179, v64
	ds_read_b128 v[204:207], v57 offset:7952
	s_waitcnt lgkmcnt(6)
	v_fma_f32 v64, -v41, v180, v68
	v_fma_f32 v64, -v42, v181, v64
	v_fma_f32 v64, -v43, v182, v64
	v_fma_f32 v68, -v44, v183, v64
	ds_read_b128 v[168:171], v57 offset:7968
	s_waitcnt lgkmcnt(6)
	v_fma_f32 v64, -v45, v184, v68
	v_fma_f32 v64, -v46, v185, v64
	v_fma_f32 v64, -v47, v186, v64
	v_fma_f32 v68, -v50, v187, v64
	ds_read_b128 v[172:175], v57 offset:7984
	s_waitcnt lgkmcnt(6)
	v_fma_f32 v64, -v51, v188, v68
	v_fma_f32 v64, -v52, v189, v64
	v_fma_f32 v64, -v53, v190, v64
	v_fma_f32 v68, -v56, v191, v64
	ds_read_b128 v[176:179], v57 offset:8000
	s_waitcnt lgkmcnt(6)
	v_fma_f32 v64, -v58, v192, v68
	v_fma_f32 v64, -v59, v193, v64
	v_fma_f32 v64, -v60, v194, v64
	v_fma_f32 v68, -v195, v61, v64
	ds_read_b128 v[180:183], v57 offset:8016
	s_waitcnt lgkmcnt(6)
	v_fma_f32 v64, -v196, v62, v68
	ds_read_b128 v[184:187], v57 offset:8032
	v_fma_f32 v64, -v197, v63, v64
	s_waitcnt lgkmcnt(6)
	v_fma_f32 v65, -v127, v200, v81
	v_fma_f32 v65, -v26, v201, v65
	v_fma_f32 v65, -v27, v202, v65
	v_fma_f32 v65, -v30, v203, v65
	ds_read_b128 v[188:191], v57 offset:8048
	s_waitcnt lgkmcnt(6)
	v_fma_f32 v65, -v31, v204, v65
	v_fma_f32 v65, -v32, v205, v65
	v_fma_f32 v65, -v33, v206, v65
	v_fma_f32 v65, -v36, v207, v65
	ds_read_b128 v[192:195], v57 offset:8192
	s_waitcnt lgkmcnt(6)
	v_fma_f32 v65, -v37, v168, v65
	v_fma_f32 v65, -v38, v169, v65
	v_fma_f32 v65, -v39, v170, v65
	v_fma_f32 v65, -v40, v171, v65
	ds_read_b128 v[196:199], v57 offset:8208
	s_waitcnt lgkmcnt(6)
	v_fma_f32 v65, -v41, v172, v65
	v_fma_f32 v65, -v42, v173, v65
	v_fma_f32 v65, -v43, v174, v65
	v_fma_f32 v65, -v44, v175, v65
	ds_read_b128 v[200:203], v57 offset:8224
	s_waitcnt lgkmcnt(6)
	v_fma_f32 v65, -v45, v176, v65
	v_fma_f32 v65, -v46, v177, v65
	v_fma_f32 v65, -v47, v178, v65
	v_fma_f32 v65, -v50, v179, v65
	ds_read_b128 v[204:207], v57 offset:8240
	s_waitcnt lgkmcnt(6)
	v_fma_f32 v65, -v51, v180, v65
	v_fma_f32 v65, -v52, v181, v65
	v_fma_f32 v65, -v53, v182, v65
	v_fma_f32 v65, -v56, v183, v65
	ds_read_b128 v[168:171], v57 offset:8256
	s_waitcnt lgkmcnt(6)
	v_fma_f32 v65, -v58, v184, v65
	v_fma_f32 v65, -v59, v185, v65
	v_fma_f32 v65, -v60, v186, v65
	v_fma_f32 v65, -v61, v187, v65
	ds_read_b128 v[172:175], v57 offset:8272
	s_waitcnt lgkmcnt(6)
	v_fma_f32 v65, -v62, v188, v65
	v_fma_f32 v65, -v189, v63, v65
	v_fma_f32 v65, -v190, v64, v65
	ds_read_b128 v[176:179], v57 offset:8288
	s_waitcnt lgkmcnt(6)
	v_fma_f32 v54, -v127, v192, v54
	v_fma_f32 v54, -v26, v193, v54
	v_fma_f32 v54, -v27, v194, v54
	v_fma_f32 v54, -v30, v195, v54
	ds_read_b128 v[180:183], v57 offset:8304
	s_waitcnt lgkmcnt(6)
	v_fma_f32 v54, -v31, v196, v54
	v_fma_f32 v54, -v32, v197, v54
	v_fma_f32 v54, -v33, v198, v54
	v_fma_f32 v54, -v36, v199, v54
	ds_read_b128 v[184:187], v57 offset:8448
	s_waitcnt lgkmcnt(6)
	v_fma_f32 v54, -v37, v200, v54
	v_fma_f32 v54, -v38, v201, v54
	v_fma_f32 v54, -v39, v202, v54
	v_fma_f32 v54, -v40, v203, v54
	ds_read_b128 v[188:191], v57 offset:8464
	s_waitcnt lgkmcnt(6)
	v_fma_f32 v54, -v41, v204, v54
	v_fma_f32 v54, -v42, v205, v54
	v_fma_f32 v54, -v43, v206, v54
	v_fma_f32 v54, -v44, v207, v54
	ds_read_b128 v[192:195], v57 offset:8480
	s_waitcnt lgkmcnt(6)
	v_fma_f32 v54, -v45, v168, v54
	v_fma_f32 v54, -v46, v169, v54
	v_fma_f32 v54, -v47, v170, v54
	v_fma_f32 v54, -v50, v171, v54
	ds_read_b128 v[196:199], v57 offset:8496
	s_waitcnt lgkmcnt(6)
	v_fma_f32 v54, -v51, v172, v54
	v_fma_f32 v54, -v52, v173, v54
	v_fma_f32 v54, -v53, v174, v54
	v_fma_f32 v54, -v56, v175, v54
	ds_read_b128 v[200:203], v57 offset:8512
	s_waitcnt lgkmcnt(6)
	v_fma_f32 v54, -v58, v176, v54
	v_fma_f32 v54, -v59, v177, v54
	v_fma_f32 v54, -v60, v178, v54
	v_fma_f32 v54, -v61, v179, v54
	ds_read_b128 v[204:207], v57 offset:8528
	s_waitcnt lgkmcnt(6)
	v_fma_f32 v54, -v62, v180, v54
	v_fma_f32 v54, -v63, v181, v54
	v_fma_f32 v54, -v182, v64, v54
	v_fma_f32 v54, -v183, v65, v54
	ds_read_b128 v[168:171], v57 offset:8544
	s_waitcnt lgkmcnt(6)
	v_fma_f32 v55, -v127, v184, v55
	v_fma_f32 v55, -v26, v185, v55
	v_fma_f32 v55, -v27, v186, v55
	v_fma_f32 v55, -v30, v187, v55
	ds_read_b128 v[172:175], v57 offset:8560
	s_waitcnt lgkmcnt(6)
	v_fma_f32 v55, -v31, v188, v55
	v_fma_f32 v55, -v32, v189, v55
	v_fma_f32 v55, -v33, v190, v55
	v_fma_f32 v55, -v36, v191, v55
	ds_read_b128 v[176:179], v57 offset:8576
	s_waitcnt lgkmcnt(6)
	v_fma_f32 v55, -v37, v192, v55
	v_fma_f32 v55, -v38, v193, v55
	v_fma_f32 v55, -v39, v194, v55
	v_fma_f32 v55, -v40, v195, v55
	ds_read_b128 v[180:183], v57 offset:8704
	s_waitcnt lgkmcnt(6)
	v_fma_f32 v55, -v41, v196, v55
	v_fma_f32 v55, -v42, v197, v55
	v_fma_f32 v55, -v43, v198, v55
	v_fma_f32 v55, -v44, v199, v55
	ds_read_b128 v[184:187], v57 offset:8720
	s_waitcnt lgkmcnt(6)
	v_fma_f32 v55, -v45, v200, v55
	v_fma_f32 v55, -v46, v201, v55
	v_fma_f32 v55, -v47, v202, v55
	v_fma_f32 v55, -v50, v203, v55
	ds_read_b128 v[188:191], v57 offset:8736
	s_waitcnt lgkmcnt(6)
	v_fma_f32 v55, -v51, v204, v55
	v_fma_f32 v55, -v52, v205, v55
	v_fma_f32 v55, -v53, v206, v55
	v_fma_f32 v55, -v56, v207, v55
	ds_read_b128 v[192:195], v57 offset:8752
	s_waitcnt lgkmcnt(6)
	v_fma_f32 v55, -v58, v168, v55
	v_fma_f32 v55, -v59, v169, v55
	v_fma_f32 v55, -v60, v170, v55
	v_fma_f32 v55, -v61, v171, v55
	ds_read_b128 v[196:199], v57 offset:8768
	s_waitcnt lgkmcnt(6)
	v_fma_f32 v55, -v62, v172, v55
	v_fma_f32 v55, -v63, v173, v55
	v_fma_f32 v55, -v174, v64, v55
	v_fma_f32 v55, -v175, v65, v55
	ds_read_b128 v[200:203], v57 offset:8784
	s_waitcnt lgkmcnt(6)
; #define LAS __attribute__((address_space(3)))
; __device__ __forceinline__ void dn_prep_item(int item, unsigned char* ws, LAS unsigned char* lds, int tid, int lane, int wave) {
;     ...
; #pragma unroll
;         for (int i = 1; i < 64; ++i) {
;             float acc = x[i];
; #pragma unroll
;             for (int j4 = 0; j4 < (i + 3) / 4; ++j4) { const f32x4 lv = *(const LAS f32x4*)(Lh + i * 64 + 4 * j4);
; #pragma unroll
;                 for (int jj = 0; jj < 4; ++jj) if (4 * j4 + jj < i) acc -= lv[jj] * x[4 * j4 + jj]; }
;             x[i] = acc;
;         }
	v_fma_f32 v55, -v176, v54, v55
	ds_read_b128 v[204:207], v57 offset:8800
	s_waitcnt lgkmcnt(6)
	v_fma_f32 v34, -v127, v180, v34
	v_fma_f32 v34, -v26, v181, v34
	v_fma_f32 v34, -v27, v182, v34
	v_fma_f32 v34, -v30, v183, v34
	ds_read_b128 v[168:171], v57 offset:8816
	s_waitcnt lgkmcnt(6)
	v_fma_f32 v34, -v31, v184, v34
	v_fma_f32 v34, -v32, v185, v34
	v_fma_f32 v34, -v33, v186, v34
	v_fma_f32 v34, -v36, v187, v34
	ds_read_b128 v[172:175], v57 offset:8832
	s_waitcnt lgkmcnt(6)
	v_fma_f32 v34, -v37, v188, v34
	v_fma_f32 v34, -v38, v189, v34
	v_fma_f32 v34, -v39, v190, v34
	v_fma_f32 v34, -v40, v191, v34
	ds_read_b128 v[176:179], v57 offset:8960
	s_waitcnt lgkmcnt(6)
	v_fma_f32 v34, -v41, v192, v34
	v_fma_f32 v34, -v42, v193, v34
	v_fma_f32 v34, -v43, v194, v34
	v_fma_f32 v34, -v44, v195, v34
	ds_read_b128 v[180:183], v57 offset:8976
	s_waitcnt lgkmcnt(6)
	v_fma_f32 v34, -v45, v196, v34
	v_fma_f32 v34, -v46, v197, v34
	v_fma_f32 v34, -v47, v198, v34
	v_fma_f32 v34, -v50, v199, v34
	ds_read_b128 v[184:187], v57 offset:8992
	s_waitcnt lgkmcnt(6)
	v_fma_f32 v34, -v51, v200, v34
	v_fma_f32 v34, -v52, v201, v34
	v_fma_f32 v34, -v53, v202, v34
	v_fma_f32 v34, -v56, v203, v34
	ds_read_b128 v[188:191], v57 offset:9008
	s_waitcnt lgkmcnt(6)
	v_fma_f32 v34, -v58, v204, v34
	v_fma_f32 v34, -v59, v205, v34
	v_fma_f32 v34, -v60, v206, v34
	v_fma_f32 v34, -v61, v207, v34
	ds_read_b128 v[192:195], v57 offset:9024
	s_waitcnt lgkmcnt(6)
	v_fma_f32 v34, -v62, v168, v34
	v_fma_f32 v34, -v63, v169, v34
	v_fma_f32 v34, -v64, v170, v34
	v_fma_f32 v34, -v171, v65, v34
	ds_read_b128 v[196:199], v57 offset:9040
	s_waitcnt lgkmcnt(6)
	v_fma_f32 v34, -v172, v54, v34
	v_fma_f32 v34, -v173, v55, v34
	ds_read_b128 v[200:203], v57 offset:9056
	s_waitcnt lgkmcnt(6)
	v_fma_f32 v35, -v127, v176, v35
	v_fma_f32 v35, -v26, v177, v35
	v_fma_f32 v35, -v27, v178, v35
	v_fma_f32 v35, -v30, v179, v35
	ds_read_b128 v[204:207], v57 offset:9072
	s_waitcnt lgkmcnt(6)
	v_fma_f32 v35, -v31, v180, v35
	v_fma_f32 v35, -v32, v181, v35
	v_fma_f32 v35, -v33, v182, v35
	v_fma_f32 v35, -v36, v183, v35
	ds_read_b128 v[168:171], v57 offset:9088
	s_waitcnt lgkmcnt(6)
	v_fma_f32 v35, -v37, v184, v35
	v_fma_f32 v35, -v38, v185, v35
	v_fma_f32 v35, -v39, v186, v35
	v_fma_f32 v35, -v40, v187, v35
	ds_read_b128 v[172:175], v57 offset:9216
	s_waitcnt lgkmcnt(6)
	v_fma_f32 v35, -v41, v188, v35
	v_fma_f32 v35, -v42, v189, v35
	v_fma_f32 v35, -v43, v190, v35
	v_fma_f32 v35, -v44, v191, v35
	ds_read_b128 v[176:179], v57 offset:9232
	s_waitcnt lgkmcnt(6)
	v_fma_f32 v35, -v45, v192, v35
	v_fma_f32 v35, -v46, v193, v35
	v_fma_f32 v35, -v47, v194, v35
	v_fma_f32 v35, -v50, v195, v35
	ds_read_b128 v[180:183], v57 offset:9248
	s_waitcnt lgkmcnt(6)
	v_fma_f32 v35, -v51, v196, v35
	v_fma_f32 v35, -v52, v197, v35
	v_fma_f32 v35, -v53, v198, v35
	v_fma_f32 v35, -v56, v199, v35
	ds_read_b128 v[184:187], v57 offset:9264
	s_waitcnt lgkmcnt(6)
	v_fma_f32 v35, -v58, v200, v35
	v_fma_f32 v35, -v59, v201, v35
	v_fma_f32 v35, -v60, v202, v35
	v_fma_f32 v35, -v61, v203, v35
	ds_read_b128 v[188:191], v57 offset:9280
	s_waitcnt lgkmcnt(6)
	v_fma_f32 v35, -v62, v204, v35
	v_fma_f32 v35, -v63, v205, v35
	v_fma_f32 v35, -v64, v206, v35
	v_fma_f32 v35, -v65, v207, v35
	ds_read_b128 v[192:195], v57 offset:9296
	s_waitcnt lgkmcnt(6)
	v_fma_f32 v35, -v54, v168, v35
	v_fma_f32 v35, -v169, v55, v35
	v_fma_f32 v35, -v170, v34, v35
	ds_read_b128 v[196:199], v57 offset:9312
	s_waitcnt lgkmcnt(6)
	v_fma_f32 v48, -v127, v172, v48
	v_fma_f32 v48, -v26, v173, v48
	v_fma_f32 v48, -v27, v174, v48
	v_fma_f32 v48, -v30, v175, v48
	ds_read_b128 v[200:203], v57 offset:9328
	s_waitcnt lgkmcnt(6)
	v_fma_f32 v48, -v31, v176, v48
	v_fma_f32 v48, -v32, v177, v48
	v_fma_f32 v48, -v33, v178, v48
	v_fma_f32 v48, -v36, v179, v48
	ds_read_b128 v[204:207], v57 offset:9344
	s_waitcnt lgkmcnt(6)
	v_fma_f32 v48, -v37, v180, v48
	v_fma_f32 v48, -v38, v181, v48
	v_fma_f32 v48, -v39, v182, v48
	v_fma_f32 v48, -v40, v183, v48
	ds_read_b128 v[168:171], v57 offset:9472
	s_waitcnt lgkmcnt(6)
	v_fma_f32 v48, -v41, v184, v48
	v_fma_f32 v48, -v42, v185, v48
	v_fma_f32 v48, -v43, v186, v48
	v_fma_f32 v48, -v44, v187, v48
	ds_read_b128 v[172:175], v57 offset:9488
	s_waitcnt lgkmcnt(6)
	v_fma_f32 v48, -v45, v188, v48
	v_fma_f32 v48, -v46, v189, v48
	v_fma_f32 v48, -v47, v190, v48
	v_fma_f32 v48, -v50, v191, v48
	ds_read_b128 v[176:179], v57 offset:9504
	s_waitcnt lgkmcnt(6)
	v_fma_f32 v48, -v51, v192, v48
	v_fma_f32 v48, -v52, v193, v48
	v_fma_f32 v48, -v53, v194, v48
	v_fma_f32 v48, -v56, v195, v48
	ds_read_b128 v[180:183], v57 offset:9520
	s_waitcnt lgkmcnt(6)
	v_fma_f32 v48, -v58, v196, v48
	v_fma_f32 v48, -v59, v197, v48
	v_fma_f32 v48, -v60, v198, v48
	v_fma_f32 v48, -v61, v199, v48
	ds_read_b128 v[184:187], v57 offset:9536
	s_waitcnt lgkmcnt(6)
	v_fma_f32 v48, -v62, v200, v48
	v_fma_f32 v48, -v63, v201, v48
	v_fma_f32 v48, -v64, v202, v48
	v_fma_f32 v48, -v65, v203, v48
	ds_read_b128 v[188:191], v57 offset:9552
	s_waitcnt lgkmcnt(6)
	v_fma_f32 v48, -v54, v204, v48
	v_fma_f32 v48, -v55, v205, v48
	v_fma_f32 v48, -v206, v34, v48
	v_fma_f32 v48, -v207, v35, v48
	ds_read_b128 v[192:195], v57 offset:9568
	s_waitcnt lgkmcnt(6)
	v_fma_f32 v49, -v127, v168, v49
	v_fma_f32 v49, -v26, v169, v49
	v_fma_f32 v49, -v27, v170, v49
	v_fma_f32 v49, -v30, v171, v49
	ds_read_b128 v[196:199], v57 offset:9584
	s_waitcnt lgkmcnt(6)
	v_fma_f32 v49, -v31, v172, v49
	v_fma_f32 v49, -v32, v173, v49
	v_fma_f32 v49, -v33, v174, v49
	v_fma_f32 v49, -v36, v175, v49
	ds_read_b128 v[200:203], v57 offset:9600
	s_waitcnt lgkmcnt(6)
; #define LAS __attribute__((address_space(3)))
; __device__ __forceinline__ void dn_prep_item(int item, unsigned char* ws, LAS unsigned char* lds, int tid, int lane, int wave) {
;     ...
; #pragma unroll
;         for (int i = 1; i < 64; ++i) {
;             float acc = x[i];
; #pragma unroll
;             for (int j4 = 0; j4 < (i + 3) / 4; ++j4) { const f32x4 lv = *(const LAS f32x4*)(Lh + i * 64 + 4 * j4);
; #pragma unroll
;                 for (int jj = 0; jj < 4; ++jj) if (4 * j4 + jj < i) acc -= lv[jj] * x[4 * j4 + jj]; }
;             x[i] = acc;
;         }
	v_fma_f32 v49, -v37, v176, v49
	v_fma_f32 v49, -v38, v177, v49
	v_fma_f32 v49, -v39, v178, v49
	v_fma_f32 v49, -v40, v179, v49
	ds_read_b128 v[204:207], v57 offset:9616
	s_waitcnt lgkmcnt(6)
	v_fma_f32 v49, -v41, v180, v49
	v_fma_f32 v49, -v42, v181, v49
	v_fma_f32 v49, -v43, v182, v49
	v_fma_f32 v49, -v44, v183, v49
	ds_read_b128 v[168:171], v57 offset:9728
	s_waitcnt lgkmcnt(6)
	v_fma_f32 v49, -v45, v184, v49
	v_fma_f32 v49, -v46, v185, v49
	v_fma_f32 v49, -v47, v186, v49
	v_fma_f32 v49, -v50, v187, v49
	ds_read_b128 v[172:175], v57 offset:9744
	s_waitcnt lgkmcnt(6)
	v_fma_f32 v49, -v51, v188, v49
	v_fma_f32 v49, -v52, v189, v49
	v_fma_f32 v49, -v53, v190, v49
	v_fma_f32 v49, -v56, v191, v49
	ds_read_b128 v[176:179], v57 offset:9760
	s_waitcnt lgkmcnt(6)
	v_fma_f32 v49, -v58, v192, v49
	v_fma_f32 v49, -v59, v193, v49
	v_fma_f32 v49, -v60, v194, v49
	v_fma_f32 v49, -v61, v195, v49
	ds_read_b128 v[180:183], v57 offset:9776
	s_waitcnt lgkmcnt(6)
	v_fma_f32 v49, -v62, v196, v49
	v_fma_f32 v49, -v63, v197, v49
	v_fma_f32 v49, -v64, v198, v49
	v_fma_f32 v49, -v65, v199, v49
	ds_read_b128 v[184:187], v57 offset:9792
	s_waitcnt lgkmcnt(6)
	v_fma_f32 v49, -v54, v200, v49
	v_fma_f32 v49, -v55, v201, v49
	v_fma_f32 v49, -v202, v34, v49
	v_fma_f32 v49, -v203, v35, v49
	ds_read_b128 v[188:191], v57 offset:9808
	s_waitcnt lgkmcnt(6)
	v_fma_f32 v49, -v204, v48, v49
	ds_read_b128 v[192:195], v57 offset:9824
	s_waitcnt lgkmcnt(6)
	v_fma_f32 v28, -v127, v168, v28
	v_fma_f32 v28, -v26, v169, v28
	v_fma_f32 v28, -v27, v170, v28
	v_fma_f32 v28, -v30, v171, v28
	ds_read_b128 v[196:199], v57 offset:9840
	s_waitcnt lgkmcnt(6)
	v_fma_f32 v28, -v31, v172, v28
	v_fma_f32 v28, -v32, v173, v28
	v_fma_f32 v28, -v33, v174, v28
	v_fma_f32 v28, -v36, v175, v28
	ds_read_b128 v[200:203], v57 offset:9856
	s_waitcnt lgkmcnt(6)
	v_fma_f32 v28, -v37, v176, v28
	v_fma_f32 v28, -v38, v177, v28
	v_fma_f32 v28, -v39, v178, v28
	v_fma_f32 v28, -v40, v179, v28
	ds_read_b128 v[204:207], v57 offset:9872
	s_waitcnt lgkmcnt(6)
	v_fma_f32 v28, -v41, v180, v28
	v_fma_f32 v28, -v42, v181, v28
	v_fma_f32 v28, -v43, v182, v28
	v_fma_f32 v28, -v44, v183, v28
	ds_read_b128 v[168:171], v57 offset:9984
	s_waitcnt lgkmcnt(6)
	v_fma_f32 v28, -v45, v184, v28
	v_fma_f32 v28, -v46, v185, v28
	v_fma_f32 v28, -v47, v186, v28
	v_fma_f32 v28, -v50, v187, v28
	ds_read_b128 v[172:175], v57 offset:10000
	s_waitcnt lgkmcnt(6)
	v_fma_f32 v28, -v51, v188, v28
	v_fma_f32 v28, -v52, v189, v28
	v_fma_f32 v28, -v53, v190, v28
	v_fma_f32 v28, -v56, v191, v28
	ds_read_b128 v[176:179], v57 offset:10016
	s_waitcnt lgkmcnt(6)
	v_fma_f32 v28, -v58, v192, v28
	v_fma_f32 v28, -v59, v193, v28
	v_fma_f32 v28, -v60, v194, v28
	v_fma_f32 v28, -v61, v195, v28
	ds_read_b128 v[180:183], v57 offset:10032
	s_waitcnt lgkmcnt(6)
	v_fma_f32 v28, -v62, v196, v28
	v_fma_f32 v28, -v63, v197, v28
	v_fma_f32 v28, -v64, v198, v28
	v_fma_f32 v28, -v65, v199, v28
	ds_read_b128 v[184:187], v57 offset:10048
	s_waitcnt lgkmcnt(6)
	v_fma_f32 v28, -v54, v200, v28
	v_fma_f32 v28, -v55, v201, v28
	v_fma_f32 v28, -v34, v202, v28
	v_fma_f32 v28, -v203, v35, v28
	ds_read_b128 v[188:191], v57 offset:10064
	s_waitcnt lgkmcnt(6)
	v_fma_f32 v28, -v204, v48, v28
	v_fma_f32 v28, -v205, v49, v28
	ds_read_b128 v[192:195], v57 offset:10080
	s_waitcnt lgkmcnt(6)
	v_fma_f32 v29, -v127, v168, v29
	v_fma_f32 v29, -v26, v169, v29
	v_fma_f32 v29, -v27, v170, v29
	v_fma_f32 v29, -v30, v171, v29
	ds_read_b128 v[196:199], v57 offset:10096
	s_waitcnt lgkmcnt(6)
	v_fma_f32 v29, -v31, v172, v29
	v_fma_f32 v29, -v32, v173, v29
	v_fma_f32 v29, -v33, v174, v29
	v_fma_f32 v29, -v36, v175, v29
	ds_read_b128 v[200:203], v57 offset:10112
	s_waitcnt lgkmcnt(6)
	v_fma_f32 v29, -v37, v176, v29
	v_fma_f32 v29, -v38, v177, v29
	v_fma_f32 v29, -v39, v178, v29
	v_fma_f32 v29, -v40, v179, v29
	ds_read_b128 v[204:207], v57 offset:10128
	s_waitcnt lgkmcnt(6)
	v_fma_f32 v29, -v41, v180, v29
	v_fma_f32 v29, -v42, v181, v29
	v_fma_f32 v29, -v43, v182, v29
	v_fma_f32 v29, -v44, v183, v29
	ds_read_b128 v[168:171], v57 offset:10240
	s_waitcnt lgkmcnt(6)
	v_fma_f32 v29, -v45, v184, v29
	v_fma_f32 v29, -v46, v185, v29
	v_fma_f32 v29, -v47, v186, v29
	v_fma_f32 v29, -v50, v187, v29
	ds_read_b128 v[172:175], v57 offset:10256
	s_waitcnt lgkmcnt(6)
	v_fma_f32 v29, -v51, v188, v29
	v_fma_f32 v29, -v52, v189, v29
	v_fma_f32 v29, -v53, v190, v29
	v_fma_f32 v29, -v56, v191, v29
	ds_read_b128 v[176:179], v57 offset:10272
	s_waitcnt lgkmcnt(6)
	v_fma_f32 v29, -v58, v192, v29
	v_fma_f32 v29, -v59, v193, v29
	v_fma_f32 v29, -v60, v194, v29
	v_fma_f32 v29, -v61, v195, v29
	ds_read_b128 v[180:183], v57 offset:10288
	s_waitcnt lgkmcnt(6)
	v_fma_f32 v29, -v62, v196, v29
	v_fma_f32 v29, -v63, v197, v29
	v_fma_f32 v29, -v64, v198, v29
	v_fma_f32 v29, -v65, v199, v29
	ds_read_b128 v[184:187], v57 offset:10304
	s_waitcnt lgkmcnt(6)
	v_fma_f32 v29, -v54, v200, v29
	v_fma_f32 v29, -v55, v201, v29
	v_fma_f32 v29, -v34, v202, v29
	v_fma_f32 v29, -v35, v203, v29
	ds_read_b128 v[188:191], v57 offset:10320
	s_waitcnt lgkmcnt(6)
	v_fma_f32 v29, -v48, v204, v29
	v_fma_f32 v29, -v205, v49, v29
	v_fma_f32 v29, -v206, v28, v29
	ds_read_b128 v[192:195], v57 offset:10336
	s_waitcnt lgkmcnt(6)
	v_fma_f32 v24, -v127, v168, v24
	v_fma_f32 v24, -v26, v169, v24
	v_fma_f32 v24, -v27, v170, v24
	v_fma_f32 v24, -v30, v171, v24
	ds_read_b128 v[196:199], v57 offset:10352
	s_waitcnt lgkmcnt(6)
	v_fma_f32 v24, -v31, v172, v24
	v_fma_f32 v24, -v32, v173, v24
	v_fma_f32 v24, -v33, v174, v24
	v_fma_f32 v24, -v36, v175, v24
	ds_read_b128 v[200:203], v57 offset:10368
	s_waitcnt lgkmcnt(6)
; #define LAS __attribute__((address_space(3)))
; __device__ __forceinline__ void dn_prep_item(int item, unsigned char* ws, LAS unsigned char* lds, int tid, int lane, int wave) {
;     ...
; #pragma unroll
;         for (int i = 1; i < 64; ++i) {
;             float acc = x[i];
; #pragma unroll
;             for (int j4 = 0; j4 < (i + 3) / 4; ++j4) { const f32x4 lv = *(const LAS f32x4*)(Lh + i * 64 + 4 * j4);
; #pragma unroll
;                 for (int jj = 0; jj < 4; ++jj) if (4 * j4 + jj < i) acc -= lv[jj] * x[4 * j4 + jj]; }
;             x[i] = acc;
;         }
	v_fma_f32 v24, -v37, v176, v24
	v_fma_f32 v24, -v38, v177, v24
	v_fma_f32 v24, -v39, v178, v24
	v_fma_f32 v24, -v40, v179, v24
	ds_read_b128 v[204:207], v57 offset:10384
	s_waitcnt lgkmcnt(6)
	v_fma_f32 v24, -v41, v180, v24
	v_fma_f32 v24, -v42, v181, v24
	v_fma_f32 v24, -v43, v182, v24
	v_fma_f32 v24, -v44, v183, v24
	ds_read_b128 v[168:171], v57 offset:10496
	s_waitcnt lgkmcnt(6)
	v_fma_f32 v24, -v45, v184, v24
	v_fma_f32 v24, -v46, v185, v24
	v_fma_f32 v24, -v47, v186, v24
	v_fma_f32 v24, -v50, v187, v24
	ds_read_b128 v[172:175], v57 offset:10512
	s_waitcnt lgkmcnt(6)
	v_fma_f32 v24, -v51, v188, v24
	v_fma_f32 v24, -v52, v189, v24
	v_fma_f32 v24, -v53, v190, v24
	v_fma_f32 v24, -v56, v191, v24
	ds_read_b128 v[176:179], v57 offset:10528
	s_waitcnt lgkmcnt(6)
	v_fma_f32 v24, -v58, v192, v24
	v_fma_f32 v24, -v59, v193, v24
	v_fma_f32 v24, -v60, v194, v24
	v_fma_f32 v24, -v61, v195, v24
	ds_read_b128 v[180:183], v57 offset:10544
	s_waitcnt lgkmcnt(6)
	v_fma_f32 v24, -v62, v196, v24
	v_fma_f32 v24, -v63, v197, v24
	v_fma_f32 v24, -v64, v198, v24
	v_fma_f32 v24, -v65, v199, v24
	ds_read_b128 v[184:187], v57 offset:10560
	s_waitcnt lgkmcnt(6)
	v_fma_f32 v24, -v54, v200, v24
	v_fma_f32 v24, -v55, v201, v24
	v_fma_f32 v24, -v34, v202, v24
	v_fma_f32 v24, -v35, v203, v24
	ds_read_b128 v[188:191], v57 offset:10576
	s_waitcnt lgkmcnt(6)
	v_fma_f32 v24, -v48, v204, v24
	v_fma_f32 v24, -v49, v205, v24
	v_fma_f32 v24, -v206, v28, v24
	v_fma_f32 v24, -v207, v29, v24
	ds_read_b128 v[192:195], v57 offset:10592
	s_waitcnt lgkmcnt(6)
	v_fma_f32 v25, -v127, v168, v25
	v_fma_f32 v25, -v26, v169, v25
	v_fma_f32 v25, -v27, v170, v25
	v_fma_f32 v25, -v30, v171, v25
	ds_read_b128 v[196:199], v57 offset:10608
	s_waitcnt lgkmcnt(6)
	v_fma_f32 v25, -v31, v172, v25
	v_fma_f32 v25, -v32, v173, v25
	v_fma_f32 v25, -v33, v174, v25
	v_fma_f32 v25, -v36, v175, v25
	ds_read_b128 v[200:203], v57 offset:10624
	s_waitcnt lgkmcnt(6)
	v_fma_f32 v25, -v37, v176, v25
	v_fma_f32 v25, -v38, v177, v25
	v_fma_f32 v25, -v39, v178, v25
	v_fma_f32 v25, -v40, v179, v25
	ds_read_b128 v[204:207], v57 offset:10640
	s_waitcnt lgkmcnt(6)
	v_fma_f32 v25, -v41, v180, v25
	v_fma_f32 v25, -v42, v181, v25
	v_fma_f32 v25, -v43, v182, v25
	v_fma_f32 v25, -v44, v183, v25
	ds_read_b128 v[168:171], v57 offset:10656
	s_waitcnt lgkmcnt(6)
	v_fma_f32 v25, -v45, v184, v25
	v_fma_f32 v25, -v46, v185, v25
	v_fma_f32 v25, -v47, v186, v25
	v_fma_f32 v25, -v50, v187, v25
	ds_read_b128 v[172:175], v57 offset:10752
	s_waitcnt lgkmcnt(6)
	v_fma_f32 v25, -v51, v188, v25
	v_fma_f32 v25, -v52, v189, v25
	v_fma_f32 v25, -v53, v190, v25
	v_fma_f32 v25, -v56, v191, v25
	ds_read_b128 v[176:179], v57 offset:10768
	s_waitcnt lgkmcnt(6)
	v_fma_f32 v25, -v58, v192, v25
	v_fma_f32 v25, -v59, v193, v25
	v_fma_f32 v25, -v60, v194, v25
	v_fma_f32 v25, -v61, v195, v25
	ds_read_b128 v[180:183], v57 offset:10784
	s_waitcnt lgkmcnt(6)
	v_fma_f32 v25, -v62, v196, v25
	v_fma_f32 v25, -v63, v197, v25
	v_fma_f32 v25, -v64, v198, v25
	v_fma_f32 v25, -v65, v199, v25
	ds_read_b128 v[184:187], v57 offset:10800
	s_waitcnt lgkmcnt(6)
	v_fma_f32 v25, -v54, v200, v25
	v_fma_f32 v25, -v55, v201, v25
	v_fma_f32 v25, -v34, v202, v25
	v_fma_f32 v25, -v35, v203, v25
	ds_read_b128 v[188:191], v57 offset:10816
	s_waitcnt lgkmcnt(6)
	v_fma_f32 v25, -v48, v204, v25
	v_fma_f32 v25, -v49, v205, v25
	v_fma_f32 v25, -v206, v28, v25
	v_fma_f32 v25, -v207, v29, v25
	ds_read_b128 v[192:195], v57 offset:10832
	s_waitcnt lgkmcnt(6)
	v_fma_f32 v25, -v168, v24, v25
	ds_read_b128 v[196:199], v57 offset:10848
	s_waitcnt lgkmcnt(6)
	v_fma_f32 v20, -v127, v172, v20
	v_fma_f32 v20, -v26, v173, v20
	v_fma_f32 v20, -v27, v174, v20
	v_fma_f32 v20, -v30, v175, v20
	ds_read_b128 v[200:203], v57 offset:10864
	s_waitcnt lgkmcnt(6)
	v_fma_f32 v20, -v31, v176, v20
	v_fma_f32 v20, -v32, v177, v20
	v_fma_f32 v20, -v33, v178, v20
	v_fma_f32 v20, -v36, v179, v20
	ds_read_b128 v[204:207], v57 offset:10880
	s_waitcnt lgkmcnt(6)
	v_fma_f32 v20, -v37, v180, v20
	v_fma_f32 v20, -v38, v181, v20
	v_fma_f32 v20, -v39, v182, v20
	v_fma_f32 v20, -v40, v183, v20
	ds_read_b128 v[168:171], v57 offset:10896
	s_waitcnt lgkmcnt(6)
	v_fma_f32 v20, -v41, v184, v20
	v_fma_f32 v20, -v42, v185, v20
	v_fma_f32 v20, -v43, v186, v20
	v_fma_f32 v20, -v44, v187, v20
	ds_read_b128 v[172:175], v57 offset:10912
	s_waitcnt lgkmcnt(6)
	v_fma_f32 v20, -v45, v188, v20
	v_fma_f32 v20, -v46, v189, v20
	v_fma_f32 v20, -v47, v190, v20
	v_fma_f32 v20, -v50, v191, v20
	ds_read_b128 v[176:179], v57 offset:11008
	s_waitcnt lgkmcnt(6)
	v_fma_f32 v20, -v51, v192, v20
	v_fma_f32 v20, -v52, v193, v20
	v_fma_f32 v20, -v53, v194, v20
	v_fma_f32 v20, -v56, v195, v20
	ds_read_b128 v[180:183], v57 offset:11024
	s_waitcnt lgkmcnt(6)
	v_fma_f32 v20, -v58, v196, v20
	v_fma_f32 v20, -v59, v197, v20
	v_fma_f32 v20, -v60, v198, v20
	v_fma_f32 v20, -v61, v199, v20
	ds_read_b128 v[184:187], v57 offset:11040
	s_waitcnt lgkmcnt(6)
	v_fma_f32 v20, -v62, v200, v20
	v_fma_f32 v20, -v63, v201, v20
	v_fma_f32 v20, -v64, v202, v20
	v_fma_f32 v20, -v65, v203, v20
	ds_read_b128 v[188:191], v57 offset:11056
	s_waitcnt lgkmcnt(6)
	v_fma_f32 v20, -v54, v204, v20
	v_fma_f32 v20, -v55, v205, v20
	v_fma_f32 v20, -v34, v206, v20
	v_fma_f32 v20, -v35, v207, v20
	ds_read_b128 v[192:195], v57 offset:11072
	s_waitcnt lgkmcnt(6)
	v_fma_f32 v20, -v48, v168, v20
	v_fma_f32 v20, -v49, v169, v20
	v_fma_f32 v20, -v28, v170, v20
	v_fma_f32 v20, -v171, v29, v20
	ds_read_b128 v[196:199], v57 offset:11088
	s_waitcnt lgkmcnt(6)
	v_fma_f32 v20, -v172, v24, v20
	v_fma_f32 v20, -v173, v25, v20
	ds_read_b128 v[200:203], v57 offset:11104
	s_waitcnt lgkmcnt(6)
; #define LAS __attribute__((address_space(3)))
; __device__ __forceinline__ void dn_prep_item(int item, unsigned char* ws, LAS unsigned char* lds, int tid, int lane, int wave) {
;     ...
; #pragma unroll
;         for (int i = 1; i < 64; ++i) {
;             float acc = x[i];
; #pragma unroll
;             for (int j4 = 0; j4 < (i + 3) / 4; ++j4) { const f32x4 lv = *(const LAS f32x4*)(Lh + i * 64 + 4 * j4);
; #pragma unroll
;                 for (int jj = 0; jj < 4; ++jj) if (4 * j4 + jj < i) acc -= lv[jj] * x[4 * j4 + jj]; }
;             x[i] = acc;
;         }
	v_fma_f32 v21, -v127, v176, v21
	v_fma_f32 v21, -v26, v177, v21
	v_fma_f32 v21, -v27, v178, v21
	v_fma_f32 v21, -v30, v179, v21
	ds_read_b128 v[204:207], v57 offset:11120
	s_waitcnt lgkmcnt(6)
	v_fma_f32 v21, -v31, v180, v21
	v_fma_f32 v21, -v32, v181, v21
	v_fma_f32 v21, -v33, v182, v21
	v_fma_f32 v21, -v36, v183, v21
	ds_read_b128 v[168:171], v57 offset:11136
	s_waitcnt lgkmcnt(6)
	v_fma_f32 v21, -v37, v184, v21
	v_fma_f32 v21, -v38, v185, v21
	v_fma_f32 v21, -v39, v186, v21
	v_fma_f32 v21, -v40, v187, v21
	ds_read_b128 v[172:175], v57 offset:11152
	s_waitcnt lgkmcnt(6)
	v_fma_f32 v21, -v41, v188, v21
	v_fma_f32 v21, -v42, v189, v21
	v_fma_f32 v21, -v43, v190, v21
	v_fma_f32 v21, -v44, v191, v21
	ds_read_b128 v[176:179], v57 offset:11168
	s_waitcnt lgkmcnt(6)
	v_fma_f32 v21, -v45, v192, v21
	v_fma_f32 v21, -v46, v193, v21
	v_fma_f32 v21, -v47, v194, v21
	v_fma_f32 v21, -v50, v195, v21
	ds_read_b128 v[180:183], v57 offset:11264
	s_waitcnt lgkmcnt(6)
	v_fma_f32 v21, -v51, v196, v21
	v_fma_f32 v21, -v52, v197, v21
	v_fma_f32 v21, -v53, v198, v21
	v_fma_f32 v21, -v56, v199, v21
	ds_read_b128 v[184:187], v57 offset:11280
	s_waitcnt lgkmcnt(6)
	v_fma_f32 v21, -v58, v200, v21
	v_fma_f32 v21, -v59, v201, v21
	v_fma_f32 v21, -v60, v202, v21
	v_fma_f32 v21, -v61, v203, v21
	ds_read_b128 v[188:191], v57 offset:11296
	s_waitcnt lgkmcnt(6)
	v_fma_f32 v21, -v62, v204, v21
	v_fma_f32 v21, -v63, v205, v21
	v_fma_f32 v21, -v64, v206, v21
	v_fma_f32 v21, -v65, v207, v21
	ds_read_b128 v[192:195], v57 offset:11312
	s_waitcnt lgkmcnt(6)
	v_fma_f32 v21, -v54, v168, v21
	v_fma_f32 v21, -v55, v169, v21
	v_fma_f32 v21, -v34, v170, v21
	v_fma_f32 v21, -v35, v171, v21
	ds_read_b128 v[196:199], v57 offset:11328
	s_waitcnt lgkmcnt(6)
	v_fma_f32 v21, -v48, v172, v21
	v_fma_f32 v21, -v49, v173, v21
	v_fma_f32 v21, -v28, v174, v21
	v_fma_f32 v21, -v29, v175, v21
	ds_read_b128 v[200:203], v57 offset:11344
	s_waitcnt lgkmcnt(6)
	v_fma_f32 v21, -v24, v176, v21
	v_fma_f32 v21, -v177, v25, v21
	v_fma_f32 v21, -v178, v20, v21
	ds_read_b128 v[204:207], v57 offset:11360
	s_waitcnt lgkmcnt(6)
	v_fma_f32 v22, -v127, v180, v22
	v_fma_f32 v22, -v26, v181, v22
	v_fma_f32 v22, -v27, v182, v22
	v_fma_f32 v22, -v30, v183, v22
	ds_read_b128 v[168:171], v57 offset:11376
	s_waitcnt lgkmcnt(6)
	v_fma_f32 v22, -v31, v184, v22
	v_fma_f32 v22, -v32, v185, v22
	v_fma_f32 v22, -v33, v186, v22
	v_fma_f32 v22, -v36, v187, v22
	ds_read_b128 v[172:175], v57 offset:11392
	s_waitcnt lgkmcnt(6)
	v_fma_f32 v22, -v37, v188, v22
	v_fma_f32 v22, -v38, v189, v22
	v_fma_f32 v22, -v39, v190, v22
	v_fma_f32 v22, -v40, v191, v22
	ds_read_b128 v[176:179], v57 offset:11408
	s_waitcnt lgkmcnt(6)
	v_fma_f32 v22, -v41, v192, v22
	v_fma_f32 v22, -v42, v193, v22
	v_fma_f32 v22, -v43, v194, v22
	v_fma_f32 v22, -v44, v195, v22
	ds_read_b128 v[180:183], v57 offset:11424
	s_waitcnt lgkmcnt(6)
	v_fma_f32 v22, -v45, v196, v22
	v_fma_f32 v22, -v46, v197, v22
	v_fma_f32 v22, -v47, v198, v22
	v_fma_f32 v22, -v50, v199, v22
	ds_read_b128 v[184:187], v57 offset:11520
	s_waitcnt lgkmcnt(6)
	v_fma_f32 v22, -v51, v200, v22
	v_fma_f32 v22, -v52, v201, v22
	v_fma_f32 v22, -v53, v202, v22
	v_fma_f32 v22, -v56, v203, v22
	ds_read_b128 v[188:191], v57 offset:11536
	s_waitcnt lgkmcnt(6)
	v_fma_f32 v22, -v58, v204, v22
	v_fma_f32 v22, -v59, v205, v22
	v_fma_f32 v22, -v60, v206, v22
	v_fma_f32 v22, -v61, v207, v22
	ds_read_b128 v[192:195], v57 offset:11552
	s_waitcnt lgkmcnt(6)
	v_fma_f32 v22, -v62, v168, v22
	v_fma_f32 v22, -v63, v169, v22
	v_fma_f32 v22, -v64, v170, v22
	v_fma_f32 v22, -v65, v171, v22
	ds_read_b128 v[196:199], v57 offset:11568
	s_waitcnt lgkmcnt(6)
	v_fma_f32 v22, -v54, v172, v22
	v_fma_f32 v22, -v55, v173, v22
	v_fma_f32 v22, -v34, v174, v22
	v_fma_f32 v22, -v35, v175, v22
	ds_read_b128 v[200:203], v57 offset:11584
	s_waitcnt lgkmcnt(6)
	v_fma_f32 v22, -v48, v176, v22
	v_fma_f32 v22, -v49, v177, v22
	v_fma_f32 v22, -v28, v178, v22
	v_fma_f32 v22, -v29, v179, v22
	ds_read_b128 v[204:207], v57 offset:11600
	s_waitcnt lgkmcnt(6)
	v_fma_f32 v22, -v24, v180, v22
	v_fma_f32 v22, -v25, v181, v22
	v_fma_f32 v22, -v182, v20, v22
	v_fma_f32 v22, -v183, v21, v22
	ds_read_b128 v[168:171], v57 offset:11616
	s_waitcnt lgkmcnt(6)
	v_fma_f32 v23, -v127, v184, v23
	v_fma_f32 v23, -v26, v185, v23
	v_fma_f32 v23, -v27, v186, v23
	v_fma_f32 v23, -v30, v187, v23
	ds_read_b128 v[172:175], v57 offset:11632
	s_waitcnt lgkmcnt(6)
	v_fma_f32 v23, -v31, v188, v23
	v_fma_f32 v23, -v32, v189, v23
	v_fma_f32 v23, -v33, v190, v23
	v_fma_f32 v23, -v36, v191, v23
	ds_read_b128 v[176:179], v57 offset:11648
	s_waitcnt lgkmcnt(6)
	v_fma_f32 v23, -v37, v192, v23
	v_fma_f32 v23, -v38, v193, v23
	v_fma_f32 v23, -v39, v194, v23
	v_fma_f32 v23, -v40, v195, v23
	ds_read_b128 v[180:183], v57 offset:11664
	s_waitcnt lgkmcnt(6)
	v_fma_f32 v23, -v41, v196, v23
	v_fma_f32 v23, -v42, v197, v23
	v_fma_f32 v23, -v43, v198, v23
	v_fma_f32 v23, -v44, v199, v23
	ds_read_b128 v[184:187], v57 offset:11680
	s_waitcnt lgkmcnt(6)
	v_fma_f32 v23, -v45, v200, v23
	v_fma_f32 v23, -v46, v201, v23
	v_fma_f32 v23, -v47, v202, v23
	v_fma_f32 v23, -v50, v203, v23
	ds_read_b128 v[188:191], v57 offset:11696
	s_waitcnt lgkmcnt(6)
	v_fma_f32 v23, -v51, v204, v23
	v_fma_f32 v23, -v52, v205, v23
	v_fma_f32 v23, -v53, v206, v23
	v_fma_f32 v23, -v56, v207, v23
	ds_read_b128 v[192:195], v57 offset:11776
	s_waitcnt lgkmcnt(6)
	v_fma_f32 v23, -v58, v168, v23
	v_fma_f32 v23, -v59, v169, v23
	v_fma_f32 v23, -v60, v170, v23
	v_fma_f32 v23, -v61, v171, v23
	ds_read_b128 v[196:199], v57 offset:11792
	s_waitcnt lgkmcnt(6)
; #define LAS __attribute__((address_space(3)))
; __device__ __forceinline__ void dn_prep_item(int item, unsigned char* ws, LAS unsigned char* lds, int tid, int lane, int wave) {
;     ...
; #pragma unroll
;         for (int i = 1; i < 64; ++i) {
;             float acc = x[i];
; #pragma unroll
;             for (int j4 = 0; j4 < (i + 3) / 4; ++j4) { const f32x4 lv = *(const LAS f32x4*)(Lh + i * 64 + 4 * j4);
; #pragma unroll
;                 for (int jj = 0; jj < 4; ++jj) if (4 * j4 + jj < i) acc -= lv[jj] * x[4 * j4 + jj]; }
;             x[i] = acc;
;         }
	v_fma_f32 v23, -v62, v172, v23
	v_fma_f32 v23, -v63, v173, v23
	v_fma_f32 v23, -v64, v174, v23
	v_fma_f32 v23, -v65, v175, v23
	ds_read_b128 v[200:203], v57 offset:11808
	s_waitcnt lgkmcnt(6)
	v_fma_f32 v23, -v54, v176, v23
	v_fma_f32 v23, -v55, v177, v23
	v_fma_f32 v23, -v34, v178, v23
	v_fma_f32 v23, -v35, v179, v23
	ds_read_b128 v[204:207], v57 offset:11824
	s_waitcnt lgkmcnt(6)
	v_fma_f32 v23, -v48, v180, v23
	v_fma_f32 v23, -v49, v181, v23
	v_fma_f32 v23, -v28, v182, v23
	v_fma_f32 v23, -v29, v183, v23
	ds_read_b128 v[168:171], v57 offset:11840
	s_waitcnt lgkmcnt(6)
	v_fma_f32 v23, -v24, v184, v23
	v_fma_f32 v23, -v25, v185, v23
	v_fma_f32 v23, -v186, v20, v23
	v_fma_f32 v23, -v187, v21, v23
	ds_read_b128 v[172:175], v57 offset:11856
	s_waitcnt lgkmcnt(6)
	v_fma_f32 v23, -v188, v22, v23
	ds_read_b128 v[176:179], v57 offset:11872
	s_waitcnt lgkmcnt(6)
	v_fma_f32 v18, -v127, v192, v18
	v_fma_f32 v18, -v26, v193, v18
	v_fma_f32 v18, -v27, v194, v18
	v_fma_f32 v18, -v30, v195, v18
	ds_read_b128 v[180:183], v57 offset:11888
	s_waitcnt lgkmcnt(6)
	v_fma_f32 v18, -v31, v196, v18
	v_fma_f32 v18, -v32, v197, v18
	v_fma_f32 v18, -v33, v198, v18
	v_fma_f32 v18, -v36, v199, v18
	ds_read_b128 v[184:187], v57 offset:11904
	s_waitcnt lgkmcnt(6)
	v_fma_f32 v18, -v37, v200, v18
	v_fma_f32 v18, -v38, v201, v18
	v_fma_f32 v18, -v39, v202, v18
	v_fma_f32 v18, -v40, v203, v18
	ds_read_b128 v[188:191], v57 offset:11920
	s_waitcnt lgkmcnt(6)
	v_fma_f32 v18, -v41, v204, v18
	v_fma_f32 v18, -v42, v205, v18
	v_fma_f32 v18, -v43, v206, v18
	v_fma_f32 v18, -v44, v207, v18
	ds_read_b128 v[192:195], v57 offset:11936
	s_waitcnt lgkmcnt(6)
	v_fma_f32 v18, -v45, v168, v18
	v_fma_f32 v18, -v46, v169, v18
	v_fma_f32 v18, -v47, v170, v18
	v_fma_f32 v18, -v50, v171, v18
	ds_read_b128 v[196:199], v57 offset:11952
	s_waitcnt lgkmcnt(6)
	v_fma_f32 v18, -v51, v172, v18
	v_fma_f32 v18, -v52, v173, v18
	v_fma_f32 v18, -v53, v174, v18
	v_fma_f32 v18, -v56, v175, v18
	ds_read_b128 v[200:203], v57 offset:12032
	s_waitcnt lgkmcnt(6)
	v_fma_f32 v18, -v58, v176, v18
	v_fma_f32 v18, -v59, v177, v18
	v_fma_f32 v18, -v60, v178, v18
	v_fma_f32 v18, -v61, v179, v18
	ds_read_b128 v[204:207], v57 offset:12048
	s_waitcnt lgkmcnt(6)
	v_fma_f32 v18, -v62, v180, v18
	v_fma_f32 v18, -v63, v181, v18
	v_fma_f32 v18, -v64, v182, v18
	v_fma_f32 v18, -v65, v183, v18
	ds_read_b128 v[168:171], v57 offset:12064
	s_waitcnt lgkmcnt(6)
	v_fma_f32 v18, -v54, v184, v18
	v_fma_f32 v18, -v55, v185, v18
	v_fma_f32 v18, -v34, v186, v18
	v_fma_f32 v18, -v35, v187, v18
	ds_read_b128 v[172:175], v57 offset:12080
	s_waitcnt lgkmcnt(6)
	v_fma_f32 v18, -v48, v188, v18
	v_fma_f32 v18, -v49, v189, v18
	v_fma_f32 v18, -v28, v190, v18
	v_fma_f32 v18, -v29, v191, v18
	ds_read_b128 v[176:179], v57 offset:12096
	s_waitcnt lgkmcnt(6)
	v_fma_f32 v18, -v24, v192, v18
	v_fma_f32 v18, -v25, v193, v18
	v_fma_f32 v18, -v20, v194, v18
	v_fma_f32 v18, -v195, v21, v18
	ds_read_b128 v[180:183], v57 offset:12112
	s_waitcnt lgkmcnt(6)
	v_fma_f32 v18, -v196, v22, v18
	v_fma_f32 v18, -v197, v23, v18
	ds_read_b128 v[184:187], v57 offset:12128
	s_waitcnt lgkmcnt(6)
	v_fma_f32 v19, -v127, v200, v19
	v_fma_f32 v19, -v26, v201, v19
	v_fma_f32 v19, -v27, v202, v19
	v_fma_f32 v19, -v30, v203, v19
	ds_read_b128 v[188:191], v57 offset:12144
	s_waitcnt lgkmcnt(6)
	v_fma_f32 v19, -v31, v204, v19
	v_fma_f32 v19, -v32, v205, v19
	v_fma_f32 v19, -v33, v206, v19
	v_fma_f32 v19, -v36, v207, v19
	ds_read_b128 v[192:195], v57 offset:12160
	s_waitcnt lgkmcnt(6)
	v_fma_f32 v19, -v37, v168, v19
	v_fma_f32 v19, -v38, v169, v19
	v_fma_f32 v19, -v39, v170, v19
	v_fma_f32 v19, -v40, v171, v19
	ds_read_b128 v[196:199], v57 offset:12176
	s_waitcnt lgkmcnt(6)
	v_fma_f32 v19, -v41, v172, v19
	v_fma_f32 v19, -v42, v173, v19
	v_fma_f32 v19, -v43, v174, v19
	v_fma_f32 v19, -v44, v175, v19
	ds_read_b128 v[200:203], v57 offset:12192
	s_waitcnt lgkmcnt(6)
	v_fma_f32 v19, -v45, v176, v19
	v_fma_f32 v19, -v46, v177, v19
	v_fma_f32 v19, -v47, v178, v19
	v_fma_f32 v19, -v50, v179, v19
	ds_read_b128 v[204:207], v57 offset:12208
	s_waitcnt lgkmcnt(6)
	v_fma_f32 v19, -v51, v180, v19
	v_fma_f32 v19, -v52, v181, v19
	v_fma_f32 v19, -v53, v182, v19
	v_fma_f32 v19, -v56, v183, v19
	ds_read_b128 v[168:171], v57 offset:12288
	s_waitcnt lgkmcnt(6)
	v_fma_f32 v19, -v58, v184, v19
	v_fma_f32 v19, -v59, v185, v19
	v_fma_f32 v19, -v60, v186, v19
	v_fma_f32 v19, -v61, v187, v19
	ds_read_b128 v[172:175], v57 offset:12304
	s_waitcnt lgkmcnt(6)
	v_fma_f32 v19, -v62, v188, v19
	v_fma_f32 v19, -v63, v189, v19
	v_fma_f32 v19, -v64, v190, v19
	v_fma_f32 v19, -v65, v191, v19
	ds_read_b128 v[176:179], v57 offset:12320
	s_waitcnt lgkmcnt(6)
	v_fma_f32 v19, -v54, v192, v19
	v_fma_f32 v19, -v55, v193, v19
	v_fma_f32 v19, -v34, v194, v19
	v_fma_f32 v19, -v35, v195, v19
	ds_read_b128 v[180:183], v57 offset:12336
	s_waitcnt lgkmcnt(6)
	v_fma_f32 v19, -v48, v196, v19
	v_fma_f32 v19, -v49, v197, v19
	v_fma_f32 v19, -v28, v198, v19
	v_fma_f32 v19, -v29, v199, v19
	ds_read_b128 v[184:187], v57 offset:12352
	s_waitcnt lgkmcnt(6)
	v_fma_f32 v19, -v24, v200, v19
	v_fma_f32 v19, -v25, v201, v19
	v_fma_f32 v19, -v20, v202, v19
	v_fma_f32 v19, -v21, v203, v19
	ds_read_b128 v[188:191], v57 offset:12368
	s_waitcnt lgkmcnt(6)
	v_fma_f32 v19, -v22, v204, v19
	v_fma_f32 v19, -v205, v23, v19
	v_fma_f32 v19, -v206, v18, v19
	ds_read_b128 v[192:195], v57 offset:12384
	s_waitcnt lgkmcnt(6)
	v_fma_f32 v16, -v127, v168, v16
	v_fma_f32 v16, -v26, v169, v16
	v_fma_f32 v16, -v27, v170, v16
	v_fma_f32 v16, -v30, v171, v16
	ds_read_b128 v[196:199], v57 offset:12400
	s_waitcnt lgkmcnt(6)
; #define LAS __attribute__((address_space(3)))
; __device__ __forceinline__ void dn_prep_item(int item, unsigned char* ws, LAS unsigned char* lds, int tid, int lane, int wave) {
;     ...
; #pragma unroll
;         for (int i = 1; i < 64; ++i) {
;             float acc = x[i];
; #pragma unroll
;             for (int j4 = 0; j4 < (i + 3) / 4; ++j4) { const f32x4 lv = *(const LAS f32x4*)(Lh + i * 64 + 4 * j4);
; #pragma unroll
;                 for (int jj = 0; jj < 4; ++jj) if (4 * j4 + jj < i) acc -= lv[jj] * x[4 * j4 + jj]; }
;             x[i] = acc;
;         }
	v_fma_f32 v16, -v31, v172, v16
	v_fma_f32 v16, -v32, v173, v16
	v_fma_f32 v16, -v33, v174, v16
	v_fma_f32 v16, -v36, v175, v16
	ds_read_b128 v[200:203], v57 offset:12416
	s_waitcnt lgkmcnt(6)
	v_fma_f32 v16, -v37, v176, v16
	v_fma_f32 v16, -v38, v177, v16
	v_fma_f32 v16, -v39, v178, v16
	v_fma_f32 v16, -v40, v179, v16
	ds_read_b128 v[204:207], v57 offset:12432
	s_waitcnt lgkmcnt(6)
	v_fma_f32 v16, -v41, v180, v16
	v_fma_f32 v16, -v42, v181, v16
	v_fma_f32 v16, -v43, v182, v16
	v_fma_f32 v16, -v44, v183, v16
	ds_read_b128 v[168:171], v57 offset:12448
	s_waitcnt lgkmcnt(6)
	v_fma_f32 v16, -v45, v184, v16
	v_fma_f32 v16, -v46, v185, v16
	v_fma_f32 v16, -v47, v186, v16
	v_fma_f32 v16, -v50, v187, v16
	ds_read_b128 v[172:175], v57 offset:12464
	s_waitcnt lgkmcnt(6)
	v_fma_f32 v16, -v51, v188, v16
	v_fma_f32 v16, -v52, v189, v16
	v_fma_f32 v16, -v53, v190, v16
	v_fma_f32 v16, -v56, v191, v16
	ds_read_b128 v[176:179], v57 offset:12544
	s_waitcnt lgkmcnt(6)
	v_fma_f32 v16, -v58, v192, v16
	v_fma_f32 v16, -v59, v193, v16
	v_fma_f32 v16, -v60, v194, v16
	v_fma_f32 v16, -v61, v195, v16
	ds_read_b128 v[180:183], v57 offset:12560
	s_waitcnt lgkmcnt(6)
	v_fma_f32 v16, -v62, v196, v16
	v_fma_f32 v16, -v63, v197, v16
	v_fma_f32 v16, -v64, v198, v16
	v_fma_f32 v16, -v65, v199, v16
	ds_read_b128 v[184:187], v57 offset:12576
	s_waitcnt lgkmcnt(6)
	v_fma_f32 v16, -v54, v200, v16
	v_fma_f32 v16, -v55, v201, v16
	v_fma_f32 v16, -v34, v202, v16
	v_fma_f32 v16, -v35, v203, v16
	ds_read_b128 v[188:191], v57 offset:12592
	s_waitcnt lgkmcnt(6)
	v_fma_f32 v16, -v48, v204, v16
	v_fma_f32 v16, -v49, v205, v16
	v_fma_f32 v16, -v28, v206, v16
	v_fma_f32 v16, -v29, v207, v16
	ds_read_b128 v[192:195], v57 offset:12608
	s_waitcnt lgkmcnt(6)
	v_fma_f32 v16, -v24, v168, v16
	v_fma_f32 v16, -v25, v169, v16
	v_fma_f32 v16, -v20, v170, v16
	v_fma_f32 v16, -v21, v171, v16
	ds_read_b128 v[196:199], v57 offset:12624
	s_waitcnt lgkmcnt(6)
	v_fma_f32 v16, -v22, v172, v16
	v_fma_f32 v16, -v23, v173, v16
	v_fma_f32 v16, -v174, v18, v16
	v_fma_f32 v16, -v175, v19, v16
	ds_read_b128 v[200:203], v57 offset:12640
	s_waitcnt lgkmcnt(6)
	v_fma_f32 v17, -v127, v176, v17
	v_fma_f32 v17, -v26, v177, v17
	v_fma_f32 v17, -v27, v178, v17
	v_fma_f32 v17, -v30, v179, v17
	ds_read_b128 v[204:207], v57 offset:12656
	s_waitcnt lgkmcnt(6)
	v_fma_f32 v17, -v31, v180, v17
	v_fma_f32 v17, -v32, v181, v17
	v_fma_f32 v17, -v33, v182, v17
	v_fma_f32 v17, -v36, v183, v17
	ds_read_b128 v[168:171], v57 offset:12672
	s_waitcnt lgkmcnt(6)
	v_fma_f32 v17, -v37, v184, v17
	v_fma_f32 v17, -v38, v185, v17
	v_fma_f32 v17, -v39, v186, v17
	v_fma_f32 v17, -v40, v187, v17
	ds_read_b128 v[172:175], v57 offset:12688
	s_waitcnt lgkmcnt(6)
	v_fma_f32 v17, -v41, v188, v17
	v_fma_f32 v17, -v42, v189, v17
	v_fma_f32 v17, -v43, v190, v17
	v_fma_f32 v17, -v44, v191, v17
	ds_read_b128 v[176:179], v57 offset:12704
	s_waitcnt lgkmcnt(6)
	v_fma_f32 v17, -v45, v192, v17
	v_fma_f32 v17, -v46, v193, v17
	v_fma_f32 v17, -v47, v194, v17
	v_fma_f32 v17, -v50, v195, v17
	ds_read_b128 v[180:183], v57 offset:12720
	s_waitcnt lgkmcnt(6)
	v_fma_f32 v17, -v51, v196, v17
	v_fma_f32 v17, -v52, v197, v17
	v_fma_f32 v17, -v53, v198, v17
	v_fma_f32 v17, -v56, v199, v17
	ds_read_b128 v[184:187], v57 offset:12736
	s_waitcnt lgkmcnt(6)
	v_fma_f32 v17, -v58, v200, v17
	v_fma_f32 v17, -v59, v201, v17
	v_fma_f32 v17, -v60, v202, v17
	v_fma_f32 v17, -v61, v203, v17
	ds_read_b128 v[188:191], v57 offset:12800
	s_waitcnt lgkmcnt(6)
	v_fma_f32 v17, -v62, v204, v17
	v_fma_f32 v17, -v63, v205, v17
	v_fma_f32 v17, -v64, v206, v17
	v_fma_f32 v17, -v65, v207, v17
	ds_read_b128 v[192:195], v57 offset:12816
	s_waitcnt lgkmcnt(6)
	v_fma_f32 v17, -v54, v168, v17
	v_fma_f32 v17, -v55, v169, v17
	v_fma_f32 v17, -v34, v170, v17
	v_fma_f32 v17, -v35, v171, v17
	ds_read_b128 v[196:199], v57 offset:12832
	s_waitcnt lgkmcnt(6)
	v_fma_f32 v17, -v48, v172, v17
	v_fma_f32 v17, -v49, v173, v17
	v_fma_f32 v17, -v28, v174, v17
	v_fma_f32 v17, -v29, v175, v17
	ds_read_b128 v[200:203], v57 offset:12848
	s_waitcnt lgkmcnt(6)
	v_fma_f32 v17, -v24, v176, v17
	v_fma_f32 v17, -v25, v177, v17
	v_fma_f32 v17, -v20, v178, v17
	v_fma_f32 v17, -v21, v179, v17
	ds_read_b128 v[204:207], v57 offset:12864
	s_waitcnt lgkmcnt(6)
	v_fma_f32 v17, -v22, v180, v17
	v_fma_f32 v17, -v23, v181, v17
	v_fma_f32 v17, -v182, v18, v17
	v_fma_f32 v17, -v183, v19, v17
	ds_read_b128 v[168:171], v57 offset:12880
	s_waitcnt lgkmcnt(6)
	v_fma_f32 v17, -v184, v16, v17
	ds_read_b128 v[172:175], v57 offset:12896
	s_waitcnt lgkmcnt(6)
	v_fma_f32 v14, -v127, v188, v14
	v_fma_f32 v14, -v26, v189, v14
	v_fma_f32 v14, -v27, v190, v14
	v_fma_f32 v14, -v30, v191, v14
	ds_read_b128 v[176:179], v57 offset:12912
	s_waitcnt lgkmcnt(6)
	v_fma_f32 v14, -v31, v192, v14
	v_fma_f32 v14, -v32, v193, v14
	v_fma_f32 v14, -v33, v194, v14
	v_fma_f32 v14, -v36, v195, v14
	ds_read_b128 v[180:183], v57 offset:12928
	s_waitcnt lgkmcnt(6)
	v_fma_f32 v14, -v37, v196, v14
	v_fma_f32 v14, -v38, v197, v14
	v_fma_f32 v14, -v39, v198, v14
	v_fma_f32 v14, -v40, v199, v14
	ds_read_b128 v[184:187], v57 offset:12944
	s_waitcnt lgkmcnt(6)
	v_fma_f32 v14, -v41, v200, v14
	v_fma_f32 v14, -v42, v201, v14
	v_fma_f32 v14, -v43, v202, v14
	v_fma_f32 v14, -v44, v203, v14
	ds_read_b128 v[188:191], v57 offset:12960
	s_waitcnt lgkmcnt(6)
	v_fma_f32 v14, -v45, v204, v14
	v_fma_f32 v14, -v46, v205, v14
	v_fma_f32 v14, -v47, v206, v14
	v_fma_f32 v14, -v50, v207, v14
	ds_read_b128 v[192:195], v57 offset:12976
	s_waitcnt lgkmcnt(6)
	v_fma_f32 v14, -v51, v168, v14
	v_fma_f32 v14, -v52, v169, v14
	v_fma_f32 v14, -v53, v170, v14
	v_fma_f32 v14, -v56, v171, v14
	ds_read_b128 v[196:199], v57 offset:12992
	s_waitcnt lgkmcnt(6)
; #define LAS __attribute__((address_space(3)))
; __device__ __forceinline__ void dn_prep_item(int item, unsigned char* ws, LAS unsigned char* lds, int tid, int lane, int wave) {
;     ...
; #pragma unroll
;         for (int i = 1; i < 64; ++i) {
;             float acc = x[i];
; #pragma unroll
;             for (int j4 = 0; j4 < (i + 3) / 4; ++j4) { const f32x4 lv = *(const LAS f32x4*)(Lh + i * 64 + 4 * j4);
; #pragma unroll
;                 for (int jj = 0; jj < 4; ++jj) if (4 * j4 + jj < i) acc -= lv[jj] * x[4 * j4 + jj]; }
;             x[i] = acc;
;         }
	v_fma_f32 v14, -v58, v172, v14
	v_fma_f32 v14, -v59, v173, v14
	v_fma_f32 v14, -v60, v174, v14
	v_fma_f32 v14, -v61, v175, v14
	ds_read_b128 v[200:203], v57 offset:13056
	s_waitcnt lgkmcnt(6)
	v_fma_f32 v14, -v62, v176, v14
	v_fma_f32 v14, -v63, v177, v14
	v_fma_f32 v14, -v64, v178, v14
	v_fma_f32 v14, -v65, v179, v14
	ds_read_b128 v[204:207], v57 offset:13072
	s_waitcnt lgkmcnt(6)
	v_fma_f32 v14, -v54, v180, v14
	v_fma_f32 v14, -v55, v181, v14
	v_fma_f32 v14, -v34, v182, v14
	v_fma_f32 v14, -v35, v183, v14
	ds_read_b128 v[168:171], v57 offset:13088
	s_waitcnt lgkmcnt(6)
	v_fma_f32 v14, -v48, v184, v14
	v_fma_f32 v14, -v49, v185, v14
	v_fma_f32 v14, -v28, v186, v14
	v_fma_f32 v14, -v29, v187, v14
	ds_read_b128 v[172:175], v57 offset:13104
	s_waitcnt lgkmcnt(6)
	v_fma_f32 v14, -v24, v188, v14
	v_fma_f32 v14, -v25, v189, v14
	v_fma_f32 v14, -v20, v190, v14
	v_fma_f32 v14, -v21, v191, v14
	ds_read_b128 v[176:179], v57 offset:13120
	s_waitcnt lgkmcnt(6)
	v_fma_f32 v14, -v22, v192, v14
	v_fma_f32 v14, -v23, v193, v14
	v_fma_f32 v14, -v18, v194, v14
	v_fma_f32 v14, -v195, v19, v14
	ds_read_b128 v[180:183], v57 offset:13136
	s_waitcnt lgkmcnt(6)
	v_fma_f32 v14, -v196, v16, v14
	v_fma_f32 v14, -v197, v17, v14
	ds_read_b128 v[184:187], v57 offset:13152
	s_waitcnt lgkmcnt(6)
	v_fma_f32 v15, -v127, v200, v15
	v_fma_f32 v15, -v26, v201, v15
	v_fma_f32 v15, -v27, v202, v15
	v_fma_f32 v15, -v30, v203, v15
	ds_read_b128 v[188:191], v57 offset:13168
	s_waitcnt lgkmcnt(6)
	v_fma_f32 v15, -v31, v204, v15
	v_fma_f32 v15, -v32, v205, v15
	v_fma_f32 v15, -v33, v206, v15
	v_fma_f32 v15, -v36, v207, v15
	ds_read_b128 v[192:195], v57 offset:13184
	s_waitcnt lgkmcnt(6)
	v_fma_f32 v15, -v37, v168, v15
	v_fma_f32 v15, -v38, v169, v15
	v_fma_f32 v15, -v39, v170, v15
	v_fma_f32 v15, -v40, v171, v15
	ds_read_b128 v[196:199], v57 offset:13200
	s_waitcnt lgkmcnt(6)
	v_fma_f32 v15, -v41, v172, v15
	v_fma_f32 v15, -v42, v173, v15
	v_fma_f32 v15, -v43, v174, v15
	v_fma_f32 v15, -v44, v175, v15
	ds_read_b128 v[200:203], v57 offset:13216
	s_waitcnt lgkmcnt(6)
	v_fma_f32 v15, -v45, v176, v15
	v_fma_f32 v15, -v46, v177, v15
	v_fma_f32 v15, -v47, v178, v15
	v_fma_f32 v15, -v50, v179, v15
	ds_read_b128 v[204:207], v57 offset:13232
	s_waitcnt lgkmcnt(6)
	v_fma_f32 v15, -v51, v180, v15
	v_fma_f32 v15, -v52, v181, v15
	v_fma_f32 v15, -v53, v182, v15
	v_fma_f32 v15, -v56, v183, v15
	ds_read_b128 v[168:171], v57 offset:13248
	s_waitcnt lgkmcnt(6)
	v_fma_f32 v15, -v58, v184, v15
	v_fma_f32 v15, -v59, v185, v15
	v_fma_f32 v15, -v60, v186, v15
	v_fma_f32 v15, -v61, v187, v15
	ds_read_b128 v[172:175], v57 offset:13312
	s_waitcnt lgkmcnt(6)
	v_fma_f32 v15, -v62, v188, v15
	v_fma_f32 v15, -v63, v189, v15
	v_fma_f32 v15, -v64, v190, v15
	v_fma_f32 v15, -v65, v191, v15
	ds_read_b128 v[176:179], v57 offset:13328
	s_waitcnt lgkmcnt(6)
	v_fma_f32 v15, -v54, v192, v15
	v_fma_f32 v15, -v55, v193, v15
	v_fma_f32 v15, -v34, v194, v15
	v_fma_f32 v15, -v35, v195, v15
	ds_read_b128 v[180:183], v57 offset:13344
	s_waitcnt lgkmcnt(6)
	v_fma_f32 v15, -v48, v196, v15
	v_fma_f32 v15, -v49, v197, v15
	v_fma_f32 v15, -v28, v198, v15
	v_fma_f32 v15, -v29, v199, v15
	ds_read_b128 v[184:187], v57 offset:13360
	s_waitcnt lgkmcnt(6)
	v_fma_f32 v15, -v24, v200, v15
	v_fma_f32 v15, -v25, v201, v15
	v_fma_f32 v15, -v20, v202, v15
	v_fma_f32 v15, -v21, v203, v15
	ds_read_b128 v[188:191], v57 offset:13376
	s_waitcnt lgkmcnt(6)
	v_fma_f32 v15, -v22, v204, v15
	v_fma_f32 v15, -v23, v205, v15
	v_fma_f32 v15, -v18, v206, v15
	v_fma_f32 v15, -v19, v207, v15
	ds_read_b128 v[192:195], v57 offset:13392
	s_waitcnt lgkmcnt(6)
	v_fma_f32 v15, -v16, v168, v15
	v_fma_f32 v15, -v169, v17, v15
	v_fma_f32 v15, -v170, v14, v15
	ds_read_b128 v[196:199], v57 offset:13408
	s_waitcnt lgkmcnt(6)
	v_fma_f32 v12, -v127, v172, v12
	v_fma_f32 v12, -v26, v173, v12
	v_fma_f32 v12, -v27, v174, v12
	v_fma_f32 v12, -v30, v175, v12
	ds_read_b128 v[200:203], v57 offset:13424
	s_waitcnt lgkmcnt(6)
	v_fma_f32 v12, -v31, v176, v12
	v_fma_f32 v12, -v32, v177, v12
	v_fma_f32 v12, -v33, v178, v12
	v_fma_f32 v12, -v36, v179, v12
	ds_read_b128 v[204:207], v57 offset:13440
	s_waitcnt lgkmcnt(6)
	v_fma_f32 v12, -v37, v180, v12
	v_fma_f32 v12, -v38, v181, v12
	v_fma_f32 v12, -v39, v182, v12
	v_fma_f32 v12, -v40, v183, v12
	ds_read_b128 v[168:171], v57 offset:13456
	s_waitcnt lgkmcnt(6)
	v_fma_f32 v12, -v41, v184, v12
	v_fma_f32 v12, -v42, v185, v12
	v_fma_f32 v12, -v43, v186, v12
	v_fma_f32 v12, -v44, v187, v12
	ds_read_b128 v[172:175], v57 offset:13472
	s_waitcnt lgkmcnt(6)
	v_fma_f32 v12, -v45, v188, v12
	v_fma_f32 v12, -v46, v189, v12
	v_fma_f32 v12, -v47, v190, v12
	v_fma_f32 v12, -v50, v191, v12
	ds_read_b128 v[176:179], v57 offset:13488
	s_waitcnt lgkmcnt(6)
	v_fma_f32 v12, -v51, v192, v12
	v_fma_f32 v12, -v52, v193, v12
	v_fma_f32 v12, -v53, v194, v12
	v_fma_f32 v12, -v56, v195, v12
	ds_read_b128 v[180:183], v57 offset:13504
	s_waitcnt lgkmcnt(6)
	v_fma_f32 v12, -v58, v196, v12
	v_fma_f32 v12, -v59, v197, v12
	v_fma_f32 v12, -v60, v198, v12
	v_fma_f32 v12, -v61, v199, v12
	ds_read_b128 v[184:187], v57 offset:13568
	s_waitcnt lgkmcnt(6)
	v_fma_f32 v12, -v62, v200, v12
	v_fma_f32 v12, -v63, v201, v12
	v_fma_f32 v12, -v64, v202, v12
	v_fma_f32 v12, -v65, v203, v12
	ds_read_b128 v[188:191], v57 offset:13584
	s_waitcnt lgkmcnt(6)
	v_fma_f32 v12, -v54, v204, v12
	v_fma_f32 v12, -v55, v205, v12
	v_fma_f32 v12, -v34, v206, v12
	v_fma_f32 v12, -v35, v207, v12
	ds_read_b128 v[192:195], v57 offset:13600
	s_waitcnt lgkmcnt(6)
	v_fma_f32 v12, -v48, v168, v12
	v_fma_f32 v12, -v49, v169, v12
	v_fma_f32 v12, -v28, v170, v12
	v_fma_f32 v12, -v29, v171, v12
	ds_read_b128 v[196:199], v57 offset:13616
	s_waitcnt lgkmcnt(6)
; #define LAS __attribute__((address_space(3)))
; __device__ __forceinline__ void dn_prep_item(int item, unsigned char* ws, LAS unsigned char* lds, int tid, int lane, int wave) {
;     ...
; #pragma unroll
;         for (int i = 1; i < 64; ++i) {
;             float acc = x[i];
; #pragma unroll
;             for (int j4 = 0; j4 < (i + 3) / 4; ++j4) { const f32x4 lv = *(const LAS f32x4*)(Lh + i * 64 + 4 * j4);
; #pragma unroll
;                 for (int jj = 0; jj < 4; ++jj) if (4 * j4 + jj < i) acc -= lv[jj] * x[4 * j4 + jj]; }
;             x[i] = acc;
;         }
	v_fma_f32 v12, -v24, v172, v12
	v_fma_f32 v12, -v25, v173, v12
	v_fma_f32 v12, -v20, v174, v12
	v_fma_f32 v12, -v21, v175, v12
	ds_read_b128 v[200:203], v57 offset:13632
	s_waitcnt lgkmcnt(6)
	v_fma_f32 v12, -v22, v176, v12
	v_fma_f32 v12, -v23, v177, v12
	v_fma_f32 v12, -v18, v178, v12
	v_fma_f32 v12, -v19, v179, v12
	ds_read_b128 v[204:207], v57 offset:13648
	s_waitcnt lgkmcnt(6)
	v_fma_f32 v12, -v16, v180, v12
	v_fma_f32 v12, -v17, v181, v12
	v_fma_f32 v12, -v182, v14, v12
	v_fma_f32 v12, -v183, v15, v12
	ds_read_b128 v[168:171], v57 offset:13664
	s_waitcnt lgkmcnt(6)
	v_fma_f32 v13, -v127, v184, v13
	v_fma_f32 v13, -v26, v185, v13
	v_fma_f32 v13, -v27, v186, v13
	v_fma_f32 v13, -v30, v187, v13
	ds_read_b128 v[172:175], v57 offset:13680
	s_waitcnt lgkmcnt(6)
	v_fma_f32 v13, -v31, v188, v13
	v_fma_f32 v13, -v32, v189, v13
	v_fma_f32 v13, -v33, v190, v13
	v_fma_f32 v13, -v36, v191, v13
	ds_read_b128 v[176:179], v57 offset:13696
	s_waitcnt lgkmcnt(6)
	v_fma_f32 v13, -v37, v192, v13
	v_fma_f32 v13, -v38, v193, v13
	v_fma_f32 v13, -v39, v194, v13
	v_fma_f32 v13, -v40, v195, v13
	ds_read_b128 v[180:183], v57 offset:13712
	s_waitcnt lgkmcnt(6)
	v_fma_f32 v13, -v41, v196, v13
	v_fma_f32 v13, -v42, v197, v13
	v_fma_f32 v13, -v43, v198, v13
	v_fma_f32 v13, -v44, v199, v13
	ds_read_b128 v[184:187], v57 offset:13728
	s_waitcnt lgkmcnt(6)
	v_fma_f32 v13, -v45, v200, v13
	v_fma_f32 v13, -v46, v201, v13
	v_fma_f32 v13, -v47, v202, v13
	v_fma_f32 v13, -v50, v203, v13
	ds_read_b128 v[188:191], v57 offset:13744
	s_waitcnt lgkmcnt(6)
	v_fma_f32 v13, -v51, v204, v13
	v_fma_f32 v13, -v52, v205, v13
	v_fma_f32 v13, -v53, v206, v13
	v_fma_f32 v13, -v56, v207, v13
	ds_read_b128 v[192:195], v57 offset:13760
	s_waitcnt lgkmcnt(6)
	v_fma_f32 v13, -v58, v168, v13
	v_fma_f32 v13, -v59, v169, v13
	v_fma_f32 v13, -v60, v170, v13
	v_fma_f32 v13, -v61, v171, v13
	ds_read_b128 v[196:199], v57 offset:13776
	s_waitcnt lgkmcnt(6)
	v_fma_f32 v13, -v62, v172, v13
	v_fma_f32 v13, -v63, v173, v13
	v_fma_f32 v13, -v64, v174, v13
	v_fma_f32 v13, -v65, v175, v13
	ds_read_b128 v[200:203], v57 offset:13824
	s_waitcnt lgkmcnt(6)
	v_fma_f32 v13, -v54, v176, v13
	v_fma_f32 v13, -v55, v177, v13
	v_fma_f32 v13, -v34, v178, v13
	v_fma_f32 v13, -v35, v179, v13
	ds_read_b128 v[204:207], v57 offset:13840
	s_waitcnt lgkmcnt(6)
	v_fma_f32 v13, -v48, v180, v13
	v_fma_f32 v13, -v49, v181, v13
	v_fma_f32 v13, -v28, v182, v13
	v_fma_f32 v13, -v29, v183, v13
	ds_read_b128 v[168:171], v57 offset:13856
	s_waitcnt lgkmcnt(6)
	v_fma_f32 v13, -v24, v184, v13
	v_fma_f32 v13, -v25, v185, v13
	v_fma_f32 v13, -v20, v186, v13
	v_fma_f32 v13, -v21, v187, v13
	ds_read_b128 v[172:175], v57 offset:13872
	s_waitcnt lgkmcnt(6)
	v_fma_f32 v13, -v22, v188, v13
	v_fma_f32 v13, -v23, v189, v13
	v_fma_f32 v13, -v18, v190, v13
	v_fma_f32 v13, -v19, v191, v13
	ds_read_b128 v[176:179], v57 offset:13888
	s_waitcnt lgkmcnt(6)
	v_fma_f32 v13, -v16, v192, v13
	v_fma_f32 v13, -v17, v193, v13
	v_fma_f32 v13, -v194, v14, v13
	v_fma_f32 v13, -v195, v15, v13
	ds_read_b128 v[180:183], v57 offset:13904
	s_waitcnt lgkmcnt(6)
	v_fma_f32 v13, -v196, v12, v13
	ds_read_b128 v[184:187], v57 offset:13920
	s_waitcnt lgkmcnt(6)
	v_fma_f32 v10, -v127, v200, v10
	v_fma_f32 v10, -v26, v201, v10
	v_fma_f32 v10, -v27, v202, v10
	v_fma_f32 v10, -v30, v203, v10
	ds_read_b128 v[188:191], v57 offset:13936
	s_waitcnt lgkmcnt(6)
	v_fma_f32 v10, -v31, v204, v10
	v_fma_f32 v10, -v32, v205, v10
	v_fma_f32 v10, -v33, v206, v10
	v_fma_f32 v10, -v36, v207, v10
	ds_read_b128 v[192:195], v57 offset:13952
	s_waitcnt lgkmcnt(6)
	v_fma_f32 v10, -v37, v168, v10
	v_fma_f32 v10, -v38, v169, v10
	v_fma_f32 v10, -v39, v170, v10
	v_fma_f32 v10, -v40, v171, v10
	ds_read_b128 v[196:199], v57 offset:13968
	s_waitcnt lgkmcnt(6)
	v_fma_f32 v10, -v41, v172, v10
	v_fma_f32 v10, -v42, v173, v10
	v_fma_f32 v10, -v43, v174, v10
	v_fma_f32 v10, -v44, v175, v10
	ds_read_b128 v[200:203], v57 offset:13984
	s_waitcnt lgkmcnt(6)
	v_fma_f32 v10, -v45, v176, v10
	v_fma_f32 v10, -v46, v177, v10
	v_fma_f32 v10, -v47, v178, v10
	v_fma_f32 v10, -v50, v179, v10
	ds_read_b128 v[204:207], v57 offset:14000
	s_waitcnt lgkmcnt(6)
	v_fma_f32 v10, -v51, v180, v10
	v_fma_f32 v10, -v52, v181, v10
	v_fma_f32 v10, -v53, v182, v10
	v_fma_f32 v10, -v56, v183, v10
	ds_read_b128 v[168:171], v57 offset:14016
	s_waitcnt lgkmcnt(6)
	v_fma_f32 v10, -v58, v184, v10
	v_fma_f32 v10, -v59, v185, v10
	v_fma_f32 v10, -v60, v186, v10
	v_fma_f32 v10, -v61, v187, v10
	ds_read_b128 v[172:175], v57 offset:14032
	s_waitcnt lgkmcnt(6)
	v_fma_f32 v10, -v62, v188, v10
	v_fma_f32 v10, -v63, v189, v10
	v_fma_f32 v10, -v64, v190, v10
	v_fma_f32 v10, -v65, v191, v10
	ds_read_b128 v[176:179], v57 offset:14080
	s_waitcnt lgkmcnt(6)
	v_fma_f32 v10, -v54, v192, v10
	v_fma_f32 v10, -v55, v193, v10
	v_fma_f32 v10, -v34, v194, v10
	v_fma_f32 v10, -v35, v195, v10
	ds_read_b128 v[180:183], v57 offset:14096
	s_waitcnt lgkmcnt(6)
	v_fma_f32 v10, -v48, v196, v10
	v_fma_f32 v10, -v49, v197, v10
	v_fma_f32 v10, -v28, v198, v10
	v_fma_f32 v10, -v29, v199, v10
	ds_read_b128 v[184:187], v57 offset:14112
	s_waitcnt lgkmcnt(6)
	v_fma_f32 v10, -v24, v200, v10
	v_fma_f32 v10, -v25, v201, v10
	v_fma_f32 v10, -v20, v202, v10
	v_fma_f32 v10, -v21, v203, v10
	ds_read_b128 v[188:191], v57 offset:14128
	s_waitcnt lgkmcnt(6)
	v_fma_f32 v10, -v22, v204, v10
	v_fma_f32 v10, -v23, v205, v10
	v_fma_f32 v10, -v18, v206, v10
	v_fma_f32 v10, -v19, v207, v10
	ds_read_b128 v[192:195], v57 offset:14144
	s_waitcnt lgkmcnt(6)
	v_fma_f32 v10, -v16, v168, v10
	v_fma_f32 v10, -v17, v169, v10
	v_fma_f32 v10, -v14, v170, v10
	v_fma_f32 v10, -v171, v15, v10
	ds_read_b128 v[196:199], v57 offset:14160
	s_waitcnt lgkmcnt(6)
; #define LAS __attribute__((address_space(3)))
; __device__ __forceinline__ void dn_prep_item(int item, unsigned char* ws, LAS unsigned char* lds, int tid, int lane, int wave) {
;     ...
;         const LAS float* Lh = LM + hd * 4096;
; #pragma unroll
;         for (int i = 1; i < 64; ++i) {
;             float acc = x[i];
; #pragma unroll
;             for (int j4 = 0; j4 < (i + 3) / 4; ++j4) { const f32x4 lv = *(const LAS f32x4*)(Lh + i * 64 + 4 * j4);
; #pragma unroll
;                 for (int jj = 0; jj < 4; ++jj) if (4 * j4 + jj < i) acc -= lv[jj] * x[4 * j4 + jj]; }
;             x[i] = acc;
;         }
	v_fma_f32 v10, -v172, v12, v10
	v_fma_f32 v10, -v173, v13, v10
	ds_read_b128 v[200:203], v57 offset:14176
	s_waitcnt lgkmcnt(6)
	v_fma_f32 v11, -v127, v176, v11
	v_fma_f32 v11, -v26, v177, v11
	v_fma_f32 v11, -v27, v178, v11
	v_fma_f32 v11, -v30, v179, v11
	ds_read_b128 v[204:207], v57 offset:14192
	s_waitcnt lgkmcnt(6)
	v_fma_f32 v11, -v31, v180, v11
	v_fma_f32 v11, -v32, v181, v11
	v_fma_f32 v11, -v33, v182, v11
	v_fma_f32 v11, -v36, v183, v11
	ds_read_b128 v[168:171], v57 offset:14208
	s_waitcnt lgkmcnt(6)
	v_fma_f32 v11, -v37, v184, v11
	v_fma_f32 v11, -v38, v185, v11
	v_fma_f32 v11, -v39, v186, v11
	v_fma_f32 v11, -v40, v187, v11
	ds_read_b128 v[172:175], v57 offset:14224
	s_waitcnt lgkmcnt(6)
	v_fma_f32 v11, -v41, v188, v11
	v_fma_f32 v11, -v42, v189, v11
	v_fma_f32 v11, -v43, v190, v11
	v_fma_f32 v11, -v44, v191, v11
	ds_read_b128 v[176:179], v57 offset:14240
	s_waitcnt lgkmcnt(6)
	v_fma_f32 v11, -v45, v192, v11
	v_fma_f32 v11, -v46, v193, v11
	v_fma_f32 v11, -v47, v194, v11
	v_fma_f32 v11, -v50, v195, v11
	ds_read_b128 v[180:183], v57 offset:14256
	s_waitcnt lgkmcnt(6)
	v_fma_f32 v11, -v51, v196, v11
	v_fma_f32 v11, -v52, v197, v11
	v_fma_f32 v11, -v53, v198, v11
	v_fma_f32 v11, -v56, v199, v11
	ds_read_b128 v[184:187], v57 offset:14272
	s_waitcnt lgkmcnt(6)
	v_fma_f32 v11, -v58, v200, v11
	v_fma_f32 v11, -v59, v201, v11
	v_fma_f32 v11, -v60, v202, v11
	v_fma_f32 v11, -v61, v203, v11
	ds_read_b128 v[188:191], v57 offset:14288
	s_waitcnt lgkmcnt(6)
	v_fma_f32 v11, -v62, v204, v11
	v_fma_f32 v11, -v63, v205, v11
	v_fma_f32 v11, -v64, v206, v11
	v_fma_f32 v11, -v65, v207, v11
	ds_read_b128 v[192:195], v57 offset:14336
	s_waitcnt lgkmcnt(6)
	v_fma_f32 v11, -v54, v168, v11
	v_fma_f32 v11, -v55, v169, v11
	v_fma_f32 v11, -v34, v170, v11
	v_fma_f32 v11, -v35, v171, v11
	ds_read_b128 v[196:199], v57 offset:14352
	s_waitcnt lgkmcnt(6)
	v_fma_f32 v11, -v48, v172, v11
	v_fma_f32 v11, -v49, v173, v11
	v_fma_f32 v11, -v28, v174, v11
	v_fma_f32 v11, -v29, v175, v11
	ds_read_b128 v[200:203], v57 offset:14368
	s_waitcnt lgkmcnt(6)
	v_fma_f32 v11, -v24, v176, v11
	v_fma_f32 v11, -v25, v177, v11
	v_fma_f32 v11, -v20, v178, v11
	v_fma_f32 v11, -v21, v179, v11
	ds_read_b128 v[204:207], v57 offset:14384
	s_waitcnt lgkmcnt(6)
	v_fma_f32 v11, -v22, v180, v11
	v_fma_f32 v11, -v23, v181, v11
	v_fma_f32 v11, -v18, v182, v11
	v_fma_f32 v11, -v19, v183, v11
	ds_read_b128 v[168:171], v57 offset:14400
	s_waitcnt lgkmcnt(6)
	v_fma_f32 v11, -v16, v184, v11
	v_fma_f32 v11, -v17, v185, v11
	v_fma_f32 v11, -v14, v186, v11
	v_fma_f32 v11, -v15, v187, v11
	ds_read_b128 v[172:175], v57 offset:14416
	s_waitcnt lgkmcnt(6)
	v_fma_f32 v11, -v12, v188, v11
	v_fma_f32 v11, -v189, v13, v11
	v_fma_f32 v11, -v190, v10, v11
	ds_read_b128 v[176:179], v57 offset:14432
	s_waitcnt lgkmcnt(6)
	v_fma_f32 v8, -v127, v192, v8
	v_fma_f32 v8, -v26, v193, v8
	v_fma_f32 v8, -v27, v194, v8
	v_fma_f32 v8, -v30, v195, v8
	ds_read_b128 v[180:183], v57 offset:14448
	s_waitcnt lgkmcnt(6)
	v_fma_f32 v8, -v31, v196, v8
	v_fma_f32 v8, -v32, v197, v8
	v_fma_f32 v8, -v33, v198, v8
	v_fma_f32 v8, -v36, v199, v8
	ds_read_b128 v[184:187], v57 offset:14464
	s_waitcnt lgkmcnt(6)
	v_fma_f32 v8, -v37, v200, v8
	v_fma_f32 v8, -v38, v201, v8
	v_fma_f32 v8, -v39, v202, v8
	v_fma_f32 v8, -v40, v203, v8
	ds_read_b128 v[188:191], v57 offset:14480
	s_waitcnt lgkmcnt(6)
	v_fma_f32 v8, -v41, v204, v8
	v_fma_f32 v8, -v42, v205, v8
	v_fma_f32 v8, -v43, v206, v8
	v_fma_f32 v8, -v44, v207, v8
	ds_read_b128 v[192:195], v57 offset:14496
	s_waitcnt lgkmcnt(6)
	v_fma_f32 v8, -v45, v168, v8
	v_fma_f32 v8, -v46, v169, v8
	v_fma_f32 v8, -v47, v170, v8
	v_fma_f32 v8, -v50, v171, v8
	ds_read_b128 v[196:199], v57 offset:14512
	s_waitcnt lgkmcnt(6)
	v_fma_f32 v8, -v51, v172, v8
	v_fma_f32 v8, -v52, v173, v8
	v_fma_f32 v8, -v53, v174, v8
	v_fma_f32 v8, -v56, v175, v8
	ds_read_b128 v[200:203], v57 offset:14528
	s_waitcnt lgkmcnt(6)
	v_fma_f32 v8, -v58, v176, v8
	v_fma_f32 v8, -v59, v177, v8
	v_fma_f32 v8, -v60, v178, v8
	v_fma_f32 v8, -v61, v179, v8
	ds_read_b128 v[204:207], v57 offset:14544
	s_waitcnt lgkmcnt(6)
	v_fma_f32 v8, -v62, v180, v8
	v_fma_f32 v8, -v63, v181, v8
	v_fma_f32 v8, -v64, v182, v8
	v_fma_f32 v8, -v65, v183, v8
	ds_read_b128 v[168:171], v57 offset:14592
	s_waitcnt lgkmcnt(6)
	v_fma_f32 v8, -v54, v184, v8
	v_fma_f32 v8, -v55, v185, v8
	v_fma_f32 v8, -v34, v186, v8
	v_fma_f32 v8, -v35, v187, v8
	ds_read_b128 v[172:175], v57 offset:14608
	s_waitcnt lgkmcnt(6)
	v_fma_f32 v8, -v48, v188, v8
	v_fma_f32 v8, -v49, v189, v8
	v_fma_f32 v8, -v28, v190, v8
	v_fma_f32 v8, -v29, v191, v8
	ds_read_b128 v[176:179], v57 offset:14624
	s_waitcnt lgkmcnt(6)
	v_fma_f32 v8, -v24, v192, v8
	v_fma_f32 v8, -v25, v193, v8
	v_fma_f32 v8, -v20, v194, v8
	v_fma_f32 v8, -v21, v195, v8
	ds_read_b128 v[180:183], v57 offset:14640
	s_waitcnt lgkmcnt(6)
	v_fma_f32 v8, -v22, v196, v8
	v_fma_f32 v8, -v23, v197, v8
	v_fma_f32 v8, -v18, v198, v8
	v_fma_f32 v8, -v19, v199, v8
	ds_read_b128 v[184:187], v57 offset:14656
	s_waitcnt lgkmcnt(6)
	v_fma_f32 v8, -v16, v200, v8
	v_fma_f32 v8, -v17, v201, v8
	v_fma_f32 v8, -v14, v202, v8
	v_fma_f32 v8, -v15, v203, v8
	ds_read_b128 v[188:191], v57 offset:14672
	s_waitcnt lgkmcnt(6)
	v_fma_f32 v8, -v12, v204, v8
	v_fma_f32 v8, -v13, v205, v8
	v_fma_f32 v8, -v206, v10, v8
	v_fma_f32 v8, -v207, v11, v8
	ds_read_b128 v[192:195], v57 offset:14688
	s_waitcnt lgkmcnt(6)
	v_fma_f32 v9, -v127, v168, v9
	v_fma_f32 v9, -v26, v169, v9
	v_fma_f32 v9, -v27, v170, v9
	v_fma_f32 v9, -v30, v171, v9
	ds_read_b128 v[196:199], v57 offset:14704
	s_waitcnt lgkmcnt(6)
; #define LAS __attribute__((address_space(3)))
; __device__ __forceinline__ void dn_prep_item(int item, unsigned char* ws, LAS unsigned char* lds, int tid, int lane, int wave) {
;     ...
;         const LAS float* Lh = LM + hd * 4096;
; #pragma unroll
;         for (int i = 1; i < 64; ++i) {
;             float acc = x[i];
; #pragma unroll
;             for (int j4 = 0; j4 < (i + 3) / 4; ++j4) { const f32x4 lv = *(const LAS f32x4*)(Lh + i * 64 + 4 * j4);
; #pragma unroll
;                 for (int jj = 0; jj < 4; ++jj) if (4 * j4 + jj < i) acc -= lv[jj] * x[4 * j4 + jj]; }
;             x[i] = acc;
;         }
	v_fma_f32 v9, -v31, v172, v9
	v_fma_f32 v9, -v32, v173, v9
	v_fma_f32 v9, -v33, v174, v9
	v_fma_f32 v9, -v36, v175, v9
	ds_read_b128 v[200:203], v57 offset:14720
	s_waitcnt lgkmcnt(6)
	v_fma_f32 v9, -v37, v176, v9
	v_fma_f32 v9, -v38, v177, v9
	v_fma_f32 v9, -v39, v178, v9
	v_fma_f32 v9, -v40, v179, v9
	ds_read_b128 v[204:207], v57 offset:14736
	s_waitcnt lgkmcnt(6)
	v_fma_f32 v9, -v41, v180, v9
	v_fma_f32 v9, -v42, v181, v9
	v_fma_f32 v9, -v43, v182, v9
	v_fma_f32 v9, -v44, v183, v9
	ds_read_b128 v[168:171], v57 offset:14752
	s_waitcnt lgkmcnt(6)
	v_fma_f32 v9, -v45, v184, v9
	v_fma_f32 v9, -v46, v185, v9
	v_fma_f32 v9, -v47, v186, v9
	v_fma_f32 v9, -v50, v187, v9
	ds_read_b128 v[172:175], v57 offset:14768
	s_waitcnt lgkmcnt(6)
	v_fma_f32 v9, -v51, v188, v9
	v_fma_f32 v9, -v52, v189, v9
	v_fma_f32 v9, -v53, v190, v9
	v_fma_f32 v9, -v56, v191, v9
	ds_read_b128 v[176:179], v57 offset:14784
	s_waitcnt lgkmcnt(6)
	v_fma_f32 v9, -v58, v192, v9
	v_fma_f32 v9, -v59, v193, v9
	v_fma_f32 v9, -v60, v194, v9
	v_fma_f32 v9, -v61, v195, v9
	ds_read_b128 v[180:183], v57 offset:14800
	s_waitcnt lgkmcnt(6)
	v_fma_f32 v9, -v62, v196, v9
	v_fma_f32 v9, -v63, v197, v9
	v_fma_f32 v9, -v64, v198, v9
	v_fma_f32 v9, -v65, v199, v9
	ds_read_b128 v[184:187], v57 offset:14816
	s_waitcnt lgkmcnt(6)
	v_fma_f32 v9, -v54, v200, v9
	v_fma_f32 v9, -v55, v201, v9
	v_fma_f32 v9, -v34, v202, v9
	v_fma_f32 v9, -v35, v203, v9
	ds_read_b128 v[188:191], v57 offset:14848
	s_waitcnt lgkmcnt(6)
	v_fma_f32 v9, -v48, v204, v9
	v_fma_f32 v9, -v49, v205, v9
	v_fma_f32 v9, -v28, v206, v9
	v_fma_f32 v9, -v29, v207, v9
	ds_read_b128 v[192:195], v57 offset:14864
	s_waitcnt lgkmcnt(6)
	v_fma_f32 v9, -v24, v168, v9
	v_fma_f32 v9, -v25, v169, v9
	v_fma_f32 v9, -v20, v170, v9
	v_fma_f32 v9, -v21, v171, v9
	ds_read_b128 v[196:199], v57 offset:14880
	s_waitcnt lgkmcnt(6)
	v_fma_f32 v9, -v22, v172, v9
	v_fma_f32 v9, -v23, v173, v9
	v_fma_f32 v9, -v18, v174, v9
	v_fma_f32 v9, -v19, v175, v9
	ds_read_b128 v[200:203], v57 offset:14896
	s_waitcnt lgkmcnt(6)
	v_fma_f32 v9, -v16, v176, v9
	v_fma_f32 v9, -v17, v177, v9
	v_fma_f32 v9, -v14, v178, v9
	v_fma_f32 v9, -v15, v179, v9
	ds_read_b128 v[204:207], v57 offset:14912
	s_waitcnt lgkmcnt(6)
	v_fma_f32 v9, -v12, v180, v9
	v_fma_f32 v9, -v13, v181, v9
	v_fma_f32 v9, -v182, v10, v9
	v_fma_f32 v9, -v183, v11, v9
	ds_read_b128 v[168:171], v57 offset:14928
	s_waitcnt lgkmcnt(6)
	v_fma_f32 v9, -v184, v8, v9
	ds_read_b128 v[172:175], v57 offset:14944
	s_waitcnt lgkmcnt(6)
	v_fma_f32 v6, -v127, v188, v6
	v_fma_f32 v6, -v26, v189, v6
	v_fma_f32 v6, -v27, v190, v6
	v_fma_f32 v6, -v30, v191, v6
	ds_read_b128 v[176:179], v57 offset:14960
	s_waitcnt lgkmcnt(6)
	v_fma_f32 v6, -v31, v192, v6
	v_fma_f32 v6, -v32, v193, v6
	v_fma_f32 v6, -v33, v194, v6
	v_fma_f32 v6, -v36, v195, v6
	ds_read_b128 v[180:183], v57 offset:14976
	s_waitcnt lgkmcnt(6)
	v_fma_f32 v6, -v37, v196, v6
	v_fma_f32 v6, -v38, v197, v6
	v_fma_f32 v6, -v39, v198, v6
	v_fma_f32 v6, -v40, v199, v6
	ds_read_b128 v[184:187], v57 offset:14992
	s_waitcnt lgkmcnt(6)
	v_fma_f32 v6, -v41, v200, v6
	v_fma_f32 v6, -v42, v201, v6
	v_fma_f32 v6, -v43, v202, v6
	v_fma_f32 v6, -v44, v203, v6
	ds_read_b128 v[188:191], v57 offset:15008
	s_waitcnt lgkmcnt(6)
	v_fma_f32 v6, -v45, v204, v6
	v_fma_f32 v6, -v46, v205, v6
	v_fma_f32 v6, -v47, v206, v6
	v_fma_f32 v6, -v50, v207, v6
	ds_read_b128 v[192:195], v57 offset:15024
	s_waitcnt lgkmcnt(6)
	v_fma_f32 v6, -v51, v168, v6
	v_fma_f32 v6, -v52, v169, v6
	v_fma_f32 v6, -v53, v170, v6
	v_fma_f32 v6, -v56, v171, v6
	ds_read_b128 v[196:199], v57 offset:15040
	s_waitcnt lgkmcnt(6)
	v_fma_f32 v6, -v58, v172, v6
	v_fma_f32 v6, -v59, v173, v6
	v_fma_f32 v6, -v60, v174, v6
	v_fma_f32 v6, -v61, v175, v6
	ds_read_b128 v[200:203], v57 offset:15056
	s_waitcnt lgkmcnt(6)
	v_fma_f32 v6, -v62, v176, v6
	v_fma_f32 v6, -v63, v177, v6
	v_fma_f32 v6, -v64, v178, v6
	v_fma_f32 v6, -v65, v179, v6
	ds_read_b128 v[204:207], v57 offset:15072
	s_waitcnt lgkmcnt(6)
	v_fma_f32 v6, -v54, v180, v6
	v_fma_f32 v6, -v55, v181, v6
	v_fma_f32 v6, -v34, v182, v6
	v_fma_f32 v6, -v35, v183, v6
	ds_read_b128 v[168:171], v57 offset:15104
	s_waitcnt lgkmcnt(6)
	v_fma_f32 v6, -v48, v184, v6
	v_fma_f32 v6, -v49, v185, v6
	v_fma_f32 v6, -v28, v186, v6
	v_fma_f32 v6, -v29, v187, v6
	ds_read_b128 v[172:175], v57 offset:15120
	s_waitcnt lgkmcnt(6)
	v_fma_f32 v6, -v24, v188, v6
	v_fma_f32 v6, -v25, v189, v6
	v_fma_f32 v6, -v20, v190, v6
	v_fma_f32 v6, -v21, v191, v6
	ds_read_b128 v[176:179], v57 offset:15136
	s_waitcnt lgkmcnt(6)
	v_fma_f32 v6, -v22, v192, v6
	v_fma_f32 v6, -v23, v193, v6
	v_fma_f32 v6, -v18, v194, v6
	v_fma_f32 v6, -v19, v195, v6
	ds_read_b128 v[180:183], v57 offset:15152
	s_waitcnt lgkmcnt(6)
	v_fma_f32 v6, -v16, v196, v6
	v_fma_f32 v6, -v17, v197, v6
	v_fma_f32 v6, -v14, v198, v6
	v_fma_f32 v6, -v15, v199, v6
	ds_read_b128 v[184:187], v57 offset:15168
	s_waitcnt lgkmcnt(6)
	v_fma_f32 v6, -v12, v200, v6
	v_fma_f32 v6, -v13, v201, v6
	v_fma_f32 v6, -v10, v202, v6
	v_fma_f32 v6, -v203, v11, v6
	ds_read_b128 v[188:191], v57 offset:15184
	s_waitcnt lgkmcnt(6)
	v_fma_f32 v6, -v204, v8, v6
	v_fma_f32 v6, -v205, v9, v6
	ds_read_b128 v[192:195], v57 offset:15200
	s_waitcnt lgkmcnt(6)
	v_fma_f32 v7, -v127, v168, v7
	v_fma_f32 v7, -v26, v169, v7
	v_fma_f32 v7, -v27, v170, v7
	v_fma_f32 v7, -v30, v171, v7
	ds_read_b128 v[196:199], v57 offset:15216
	s_waitcnt lgkmcnt(6)
	v_fma_f32 v7, -v31, v172, v7
	v_fma_f32 v7, -v32, v173, v7
	v_fma_f32 v7, -v33, v174, v7
	v_fma_f32 v7, -v36, v175, v7
	ds_read_b128 v[200:203], v57 offset:15232
	s_waitcnt lgkmcnt(6)
; #define LAS __attribute__((address_space(3)))
; __device__ __forceinline__ void dn_prep_item(int item, unsigned char* ws, LAS unsigned char* lds, int tid, int lane, int wave) {
;     ...
;         const LAS float* Lh = LM + hd * 4096;
; #pragma unroll
;         for (int i = 1; i < 64; ++i) {
;             float acc = x[i];
; #pragma unroll
;             for (int j4 = 0; j4 < (i + 3) / 4; ++j4) { const f32x4 lv = *(const LAS f32x4*)(Lh + i * 64 + 4 * j4);
; #pragma unroll
;                 for (int jj = 0; jj < 4; ++jj) if (4 * j4 + jj < i) acc -= lv[jj] * x[4 * j4 + jj]; }
;             x[i] = acc;
;         }
	v_fma_f32 v7, -v37, v176, v7
	v_fma_f32 v7, -v38, v177, v7
	v_fma_f32 v7, -v39, v178, v7
	v_fma_f32 v7, -v40, v179, v7
	ds_read_b128 v[204:207], v57 offset:15248
	s_waitcnt lgkmcnt(6)
	v_fma_f32 v7, -v41, v180, v7
	v_fma_f32 v7, -v42, v181, v7
	v_fma_f32 v7, -v43, v182, v7
	v_fma_f32 v7, -v44, v183, v7
	ds_read_b128 v[168:171], v57 offset:15264
	s_waitcnt lgkmcnt(6)
	v_fma_f32 v7, -v45, v184, v7
	v_fma_f32 v7, -v46, v185, v7
	v_fma_f32 v7, -v47, v186, v7
	v_fma_f32 v7, -v50, v187, v7
	ds_read_b128 v[172:175], v57 offset:15280
	s_waitcnt lgkmcnt(6)
	v_fma_f32 v7, -v51, v188, v7
	v_fma_f32 v7, -v52, v189, v7
	v_fma_f32 v7, -v53, v190, v7
	v_fma_f32 v7, -v56, v191, v7
	ds_read_b128 v[176:179], v57 offset:15296
	s_waitcnt lgkmcnt(6)
	v_fma_f32 v7, -v58, v192, v7
	v_fma_f32 v7, -v59, v193, v7
	v_fma_f32 v7, -v60, v194, v7
	v_fma_f32 v7, -v61, v195, v7
	ds_read_b128 v[180:183], v57 offset:15312
	s_waitcnt lgkmcnt(6)
	v_fma_f32 v7, -v62, v196, v7
	v_fma_f32 v7, -v63, v197, v7
	v_fma_f32 v7, -v64, v198, v7
	v_fma_f32 v7, -v65, v199, v7
	ds_read_b128 v[184:187], v57 offset:15328
	s_waitcnt lgkmcnt(6)
	v_fma_f32 v7, -v54, v200, v7
	v_fma_f32 v7, -v55, v201, v7
	v_fma_f32 v7, -v34, v202, v7
	v_fma_f32 v7, -v35, v203, v7
	ds_read_b128 v[188:191], v57 offset:15360
	s_waitcnt lgkmcnt(6)
	v_fma_f32 v7, -v48, v204, v7
	v_fma_f32 v7, -v49, v205, v7
	v_fma_f32 v7, -v28, v206, v7
	v_fma_f32 v7, -v29, v207, v7
	ds_read_b128 v[192:195], v57 offset:15376
	s_waitcnt lgkmcnt(6)
	v_fma_f32 v7, -v24, v168, v7
	v_fma_f32 v7, -v25, v169, v7
	v_fma_f32 v7, -v20, v170, v7
	v_fma_f32 v7, -v21, v171, v7
	ds_read_b128 v[196:199], v57 offset:15392
	s_waitcnt lgkmcnt(6)
	v_fma_f32 v7, -v22, v172, v7
	v_fma_f32 v7, -v23, v173, v7
	v_fma_f32 v7, -v18, v174, v7
	v_fma_f32 v7, -v19, v175, v7
	ds_read_b128 v[200:203], v57 offset:15408
	s_waitcnt lgkmcnt(6)
	v_fma_f32 v7, -v16, v176, v7
	v_fma_f32 v7, -v17, v177, v7
	v_fma_f32 v7, -v14, v178, v7
	v_fma_f32 v7, -v15, v179, v7
	ds_read_b128 v[204:207], v57 offset:15424
	s_waitcnt lgkmcnt(6)
	v_fma_f32 v7, -v12, v180, v7
	v_fma_f32 v7, -v13, v181, v7
	v_fma_f32 v7, -v10, v182, v7
	v_fma_f32 v7, -v11, v183, v7
	ds_read_b128 v[168:171], v57 offset:15440
	s_waitcnt lgkmcnt(6)
	v_fma_f32 v7, -v8, v184, v7
	v_fma_f32 v7, -v185, v9, v7
	v_fma_f32 v7, -v186, v6, v7
	ds_read_b128 v[172:175], v57 offset:15456
	s_waitcnt lgkmcnt(6)
	v_fma_f32 v4, -v127, v188, v4
	v_fma_f32 v4, -v26, v189, v4
	v_fma_f32 v4, -v27, v190, v4
	v_fma_f32 v4, -v30, v191, v4
	ds_read_b128 v[176:179], v57 offset:15472
	s_waitcnt lgkmcnt(6)
	v_fma_f32 v4, -v31, v192, v4
	v_fma_f32 v4, -v32, v193, v4
	v_fma_f32 v4, -v33, v194, v4
	v_fma_f32 v4, -v36, v195, v4
	ds_read_b128 v[180:183], v57 offset:15488
	s_waitcnt lgkmcnt(6)
	v_fma_f32 v4, -v37, v196, v4
	v_fma_f32 v4, -v38, v197, v4
	v_fma_f32 v4, -v39, v198, v4
	v_fma_f32 v4, -v40, v199, v4
	ds_read_b128 v[184:187], v57 offset:15504
	s_waitcnt lgkmcnt(6)
	v_fma_f32 v4, -v41, v200, v4
	v_fma_f32 v4, -v42, v201, v4
	v_fma_f32 v4, -v43, v202, v4
	v_fma_f32 v4, -v44, v203, v4
	ds_read_b128 v[188:191], v57 offset:15520
	s_waitcnt lgkmcnt(6)
	v_fma_f32 v4, -v45, v204, v4
	v_fma_f32 v4, -v46, v205, v4
	v_fma_f32 v4, -v47, v206, v4
	v_fma_f32 v4, -v50, v207, v4
	ds_read_b128 v[192:195], v57 offset:15536
	s_waitcnt lgkmcnt(6)
	v_fma_f32 v4, -v51, v168, v4
	v_fma_f32 v4, -v52, v169, v4
	v_fma_f32 v4, -v53, v170, v4
	v_fma_f32 v4, -v56, v171, v4
	ds_read_b128 v[196:199], v57 offset:15552
	s_waitcnt lgkmcnt(6)
	v_fma_f32 v4, -v58, v172, v4
	v_fma_f32 v4, -v59, v173, v4
	v_fma_f32 v4, -v60, v174, v4
	v_fma_f32 v4, -v61, v175, v4
	ds_read_b128 v[200:203], v57 offset:15568
	s_waitcnt lgkmcnt(6)
	v_fma_f32 v4, -v62, v176, v4
	v_fma_f32 v4, -v63, v177, v4
	v_fma_f32 v4, -v64, v178, v4
	v_fma_f32 v4, -v65, v179, v4
	ds_read_b128 v[204:207], v57 offset:15584
	s_waitcnt lgkmcnt(6)
	v_fma_f32 v4, -v54, v180, v4
	v_fma_f32 v4, -v55, v181, v4
	v_fma_f32 v4, -v34, v182, v4
	v_fma_f32 v4, -v35, v183, v4
	ds_read_b128 v[168:171], v57 offset:15616
	s_waitcnt lgkmcnt(6)
	v_fma_f32 v4, -v48, v184, v4
	v_fma_f32 v4, -v49, v185, v4
	v_fma_f32 v4, -v28, v186, v4
	v_fma_f32 v4, -v29, v187, v4
	ds_read_b128 v[172:175], v57 offset:15632
	s_waitcnt lgkmcnt(6)
	v_fma_f32 v4, -v24, v188, v4
	v_fma_f32 v4, -v25, v189, v4
	v_fma_f32 v4, -v20, v190, v4
	v_fma_f32 v4, -v21, v191, v4
	ds_read_b128 v[176:179], v57 offset:15648
	s_waitcnt lgkmcnt(6)
	v_fma_f32 v4, -v22, v192, v4
	v_fma_f32 v4, -v23, v193, v4
	v_fma_f32 v4, -v18, v194, v4
	v_fma_f32 v4, -v19, v195, v4
	ds_read_b128 v[180:183], v57 offset:15664
	s_waitcnt lgkmcnt(6)
	v_fma_f32 v4, -v16, v196, v4
	v_fma_f32 v4, -v17, v197, v4
	v_fma_f32 v4, -v14, v198, v4
	v_fma_f32 v4, -v15, v199, v4
	ds_read_b128 v[184:187], v57 offset:15680
	s_waitcnt lgkmcnt(6)
	v_fma_f32 v4, -v12, v200, v4
	v_fma_f32 v4, -v13, v201, v4
	v_fma_f32 v4, -v10, v202, v4
	v_fma_f32 v4, -v11, v203, v4
	ds_read_b128 v[188:191], v57 offset:15696
	s_waitcnt lgkmcnt(6)
	v_fma_f32 v4, -v8, v204, v4
	v_fma_f32 v4, -v9, v205, v4
	v_fma_f32 v4, -v206, v6, v4
	v_fma_f32 v4, -v207, v7, v4
	ds_read_b128 v[192:195], v57 offset:15712
	s_waitcnt lgkmcnt(6)
	v_fma_f32 v5, -v127, v168, v5
	v_fma_f32 v5, -v26, v169, v5
	v_fma_f32 v5, -v27, v170, v5
	v_fma_f32 v5, -v30, v171, v5
	ds_read_b128 v[196:199], v57 offset:15728
	s_waitcnt lgkmcnt(6)
	v_fma_f32 v5, -v31, v172, v5
	v_fma_f32 v5, -v32, v173, v5
	v_fma_f32 v5, -v33, v174, v5
	v_fma_f32 v5, -v36, v175, v5
	ds_read_b128 v[200:203], v57 offset:15744
	s_waitcnt lgkmcnt(6)
	v_fma_f32 v5, -v37, v176, v5
	v_fma_f32 v5, -v38, v177, v5
	v_fma_f32 v5, -v39, v178, v5
	v_fma_f32 v5, -v40, v179, v5
	ds_read_b128 v[204:207], v57 offset:15760
	s_waitcnt lgkmcnt(6)
; #define LAS __attribute__((address_space(3)))
; __device__ __forceinline__ void dn_prep_item(int item, unsigned char* ws, LAS unsigned char* lds, int tid, int lane, int wave) {
;     ...
;         const LAS float* Lh = LM + hd * 4096;
; #pragma unroll
;         for (int i = 1; i < 64; ++i) {
;             float acc = x[i];
; #pragma unroll
;             for (int j4 = 0; j4 < (i + 3) / 4; ++j4) { const f32x4 lv = *(const LAS f32x4*)(Lh + i * 64 + 4 * j4);
; #pragma unroll
;                 for (int jj = 0; jj < 4; ++jj) if (4 * j4 + jj < i) acc -= lv[jj] * x[4 * j4 + jj]; }
;             x[i] = acc;
;         }
	v_fma_f32 v5, -v41, v180, v5
	v_fma_f32 v5, -v42, v181, v5
	v_fma_f32 v5, -v43, v182, v5
	v_fma_f32 v5, -v44, v183, v5
	ds_read_b128 v[168:171], v57 offset:15776
	s_waitcnt lgkmcnt(6)
	v_fma_f32 v5, -v45, v184, v5
	v_fma_f32 v5, -v46, v185, v5
	v_fma_f32 v5, -v47, v186, v5
	v_fma_f32 v5, -v50, v187, v5
	ds_read_b128 v[172:175], v57 offset:15792
	s_waitcnt lgkmcnt(6)
	v_fma_f32 v5, -v51, v188, v5
	v_fma_f32 v5, -v52, v189, v5
	v_fma_f32 v5, -v53, v190, v5
	v_fma_f32 v5, -v56, v191, v5
	ds_read_b128 v[176:179], v57 offset:15808
	s_waitcnt lgkmcnt(6)
	v_fma_f32 v5, -v58, v192, v5
	v_fma_f32 v5, -v59, v193, v5
	v_fma_f32 v5, -v60, v194, v5
	v_fma_f32 v5, -v61, v195, v5
	ds_read_b128 v[180:183], v57 offset:15824
	s_waitcnt lgkmcnt(6)
	v_fma_f32 v5, -v62, v196, v5
	v_fma_f32 v5, -v63, v197, v5
	v_fma_f32 v5, -v64, v198, v5
	v_fma_f32 v5, -v65, v199, v5
	ds_read_b128 v[184:187], v57 offset:15840
	s_waitcnt lgkmcnt(6)
	v_fma_f32 v5, -v54, v200, v5
	v_fma_f32 v5, -v55, v201, v5
	v_fma_f32 v5, -v34, v202, v5
	v_fma_f32 v5, -v35, v203, v5
	ds_read_b128 v[188:191], v57 offset:15856
	s_waitcnt lgkmcnt(6)
	v_fma_f32 v5, -v48, v204, v5
	v_fma_f32 v5, -v49, v205, v5
	v_fma_f32 v5, -v28, v206, v5
	v_fma_f32 v5, -v29, v207, v5
	ds_read_b128 v[192:195], v57 offset:15872
	s_waitcnt lgkmcnt(6)
	v_fma_f32 v5, -v24, v168, v5
	v_fma_f32 v5, -v25, v169, v5
	v_fma_f32 v5, -v20, v170, v5
	v_fma_f32 v5, -v21, v171, v5
	ds_read_b128 v[196:199], v57 offset:15888
	s_waitcnt lgkmcnt(6)
	v_fma_f32 v5, -v22, v172, v5
	v_fma_f32 v5, -v23, v173, v5
	v_fma_f32 v5, -v18, v174, v5
	v_fma_f32 v5, -v19, v175, v5
	ds_read_b128 v[200:203], v57 offset:15904
	s_waitcnt lgkmcnt(6)
	v_fma_f32 v5, -v16, v176, v5
	v_fma_f32 v5, -v17, v177, v5
	v_fma_f32 v5, -v14, v178, v5
	v_fma_f32 v5, -v15, v179, v5
	ds_read_b128 v[204:207], v57 offset:15920
	s_waitcnt lgkmcnt(6)
	v_fma_f32 v5, -v12, v180, v5
	v_fma_f32 v5, -v13, v181, v5
	v_fma_f32 v5, -v10, v182, v5
	v_fma_f32 v5, -v11, v183, v5
	ds_read_b128 v[168:171], v57 offset:15936
	s_waitcnt lgkmcnt(6)
	v_fma_f32 v5, -v8, v184, v5
	v_fma_f32 v5, -v9, v185, v5
	v_fma_f32 v5, -v186, v6, v5
	v_fma_f32 v5, -v187, v7, v5
	ds_read_b128 v[172:175], v57 offset:15952
	s_waitcnt lgkmcnt(6)
	v_fma_f32 v5, -v188, v4, v5
	ds_read_b128 v[176:179], v57 offset:15968
	s_waitcnt lgkmcnt(6)
	v_fma_f32 v2, -v127, v192, v2
	v_fma_f32 v2, -v26, v193, v2
	v_fma_f32 v2, -v27, v194, v2
	v_fma_f32 v2, -v30, v195, v2
	ds_read_b128 v[180:183], v57 offset:15984
	s_waitcnt lgkmcnt(6)
	v_fma_f32 v2, -v31, v196, v2
	v_fma_f32 v2, -v32, v197, v2
	v_fma_f32 v2, -v33, v198, v2
	v_fma_f32 v2, -v36, v199, v2
	ds_read_b128 v[184:187], v57 offset:16000
	s_waitcnt lgkmcnt(6)
	v_fma_f32 v2, -v37, v200, v2
	v_fma_f32 v2, -v38, v201, v2
	v_fma_f32 v2, -v39, v202, v2
	v_fma_f32 v2, -v40, v203, v2
	ds_read_b128 v[188:191], v57 offset:16016
	s_waitcnt lgkmcnt(6)
	v_fma_f32 v2, -v41, v204, v2
	v_fma_f32 v2, -v42, v205, v2
	v_fma_f32 v2, -v43, v206, v2
	v_fma_f32 v2, -v44, v207, v2
	ds_read_b128 v[192:195], v57 offset:16032
	s_waitcnt lgkmcnt(6)
	v_fma_f32 v2, -v45, v168, v2
	v_fma_f32 v2, -v46, v169, v2
	v_fma_f32 v2, -v47, v170, v2
	v_fma_f32 v2, -v50, v171, v2
	ds_read_b128 v[196:199], v57 offset:16048
	s_waitcnt lgkmcnt(6)
	v_fma_f32 v2, -v51, v172, v2
	v_fma_f32 v2, -v52, v173, v2
	v_fma_f32 v2, -v53, v174, v2
	v_fma_f32 v2, -v56, v175, v2
	ds_read_b128 v[200:203], v57 offset:16064
	s_waitcnt lgkmcnt(6)
	v_fma_f32 v2, -v58, v176, v2
	v_fma_f32 v2, -v59, v177, v2
	v_fma_f32 v2, -v60, v178, v2
	v_fma_f32 v2, -v61, v179, v2
	ds_read_b128 v[204:207], v57 offset:16080
	s_waitcnt lgkmcnt(6)
	v_fma_f32 v2, -v62, v180, v2
	v_fma_f32 v2, -v63, v181, v2
	v_fma_f32 v2, -v64, v182, v2
	v_fma_f32 v2, -v65, v183, v2
	ds_read_b128 v[168:171], v57 offset:16096
	s_waitcnt lgkmcnt(6)
	v_fma_f32 v2, -v54, v184, v2
	v_fma_f32 v2, -v55, v185, v2
	v_fma_f32 v2, -v34, v186, v2
	v_fma_f32 v2, -v35, v187, v2
	ds_read_b128 v[172:175], v57 offset:16112
	s_waitcnt lgkmcnt(6)
	v_fma_f32 v2, -v48, v188, v2
	v_fma_f32 v2, -v49, v189, v2
	v_fma_f32 v2, -v28, v190, v2
	v_fma_f32 v2, -v29, v191, v2
	ds_read_b128 v[176:179], v57 offset:16128
	s_waitcnt lgkmcnt(6)
	v_fma_f32 v2, -v24, v192, v2
	v_fma_f32 v2, -v25, v193, v2
	v_fma_f32 v2, -v20, v194, v2
	v_fma_f32 v2, -v21, v195, v2
	ds_read_b128 v[180:183], v57 offset:16144
	s_waitcnt lgkmcnt(6)
	v_fma_f32 v2, -v22, v196, v2
	v_fma_f32 v2, -v23, v197, v2
	v_fma_f32 v2, -v18, v198, v2
	v_fma_f32 v2, -v19, v199, v2
	ds_read_b128 v[184:187], v57 offset:16160
	s_waitcnt lgkmcnt(6)
	v_fma_f32 v2, -v16, v200, v2
	v_fma_f32 v2, -v17, v201, v2
	v_fma_f32 v2, -v14, v202, v2
	v_fma_f32 v2, -v15, v203, v2
	ds_read_b128 v[188:191], v57 offset:16176
	s_waitcnt lgkmcnt(6)
	v_fma_f32 v2, -v12, v204, v2
	v_fma_f32 v2, -v13, v205, v2
	v_fma_f32 v2, -v10, v206, v2
	v_fma_f32 v2, -v11, v207, v2
	ds_read_b128 v[192:195], v57 offset:16192
	s_waitcnt lgkmcnt(6)
	v_fma_f32 v2, -v8, v168, v2
	v_fma_f32 v2, -v9, v169, v2
	v_fma_f32 v2, -v6, v170, v2
	v_fma_f32 v2, -v171, v7, v2
	ds_read_b128 v[196:199], v57 offset:16208
	s_waitcnt lgkmcnt(6)
	v_fma_f32 v2, -v172, v4, v2
	v_fma_f32 v2, -v173, v5, v2
	ds_read_b128 v[200:203], v57 offset:16224
	s_waitcnt lgkmcnt(6)
	v_fma_f32 v3, -v127, v176, v3
	v_fma_f32 v3, -v26, v177, v3
	v_fma_f32 v3, -v27, v178, v3
	v_fma_f32 v3, -v30, v179, v3
	ds_read_b128 v[204:207], v57 offset:16240
	s_waitcnt lgkmcnt(6)
	v_fma_f32 v3, -v31, v180, v3
	v_fma_f32 v3, -v32, v181, v3
	v_fma_f32 v3, -v33, v182, v3
	v_fma_f32 v3, -v36, v183, v3
	ds_read_b128 v[168:171], v57 offset:16256
	s_waitcnt lgkmcnt(6)
; #define LAS __attribute__((address_space(3)))
; __device__ __forceinline__ void dn_prep_item(int item, unsigned char* ws, LAS unsigned char* lds, int tid, int lane, int wave) {
;     ...
;         const LAS float* Lh = LM + hd * 4096;
; #pragma unroll
;         for (int i = 1; i < 64; ++i) {
;             float acc = x[i];
; #pragma unroll
;             for (int j4 = 0; j4 < (i + 3) / 4; ++j4) { const f32x4 lv = *(const LAS f32x4*)(Lh + i * 64 + 4 * j4);
; #pragma unroll
;                 for (int jj = 0; jj < 4; ++jj) if (4 * j4 + jj < i) acc -= lv[jj] * x[4 * j4 + jj]; }
;             x[i] = acc;
;         }
	v_fma_f32 v3, -v37, v184, v3
	v_fma_f32 v3, -v38, v185, v3
	v_fma_f32 v3, -v39, v186, v3
	v_fma_f32 v3, -v40, v187, v3
	ds_read_b128 v[172:175], v57 offset:16272
	s_waitcnt lgkmcnt(6)
	v_fma_f32 v3, -v41, v188, v3
	v_fma_f32 v3, -v42, v189, v3
	v_fma_f32 v3, -v43, v190, v3
	v_fma_f32 v3, -v44, v191, v3
	ds_read_b128 v[176:179], v57 offset:16288
	s_waitcnt lgkmcnt(6)
	v_fma_f32 v3, -v45, v192, v3
	v_fma_f32 v3, -v46, v193, v3
	v_fma_f32 v3, -v47, v194, v3
	v_fma_f32 v3, -v50, v195, v3
	ds_read_b128 v[180:183], v57 offset:16304
	s_waitcnt lgkmcnt(6)
	v_fma_f32 v3, -v51, v196, v3
	v_fma_f32 v3, -v52, v197, v3
	v_fma_f32 v3, -v53, v198, v3
	v_fma_f32 v3, -v56, v199, v3
	ds_read_b128 v[184:187], v57 offset:16320
	s_waitcnt lgkmcnt(6)
	v_fma_f32 v3, -v58, v200, v3
	v_fma_f32 v3, -v59, v201, v3
	v_fma_f32 v3, -v60, v202, v3
	v_fma_f32 v3, -v61, v203, v3
	ds_read_b128 v[188:191], v57 offset:16336
	s_waitcnt lgkmcnt(6)
	v_fma_f32 v3, -v62, v204, v3
	v_fma_f32 v3, -v63, v205, v3
	v_fma_f32 v3, -v64, v206, v3
	v_fma_f32 v3, -v65, v207, v3
	ds_read_b128 v[192:195], v57 offset:16352
	s_waitcnt lgkmcnt(6)
	v_fma_f32 v3, -v54, v168, v3
	v_fma_f32 v3, -v55, v169, v3
	v_fma_f32 v3, -v34, v170, v3
	v_fma_f32 v3, -v35, v171, v3
	ds_read_b128 v[196:199], v57 offset:16368
	s_waitcnt lgkmcnt(6)
	v_fma_f32 v3, -v48, v172, v3
	v_fma_f32 v3, -v49, v173, v3
	v_fma_f32 v3, -v28, v174, v3
	v_fma_f32 v3, -v29, v175, v3
	s_waitcnt lgkmcnt(5)
	v_fma_f32 v3, -v24, v176, v3
	v_fma_f32 v3, -v25, v177, v3
	v_fma_f32 v3, -v20, v178, v3
	v_fma_f32 v3, -v21, v179, v3
	s_waitcnt lgkmcnt(4)
	v_fma_f32 v3, -v22, v180, v3
	v_fma_f32 v3, -v23, v181, v3
	v_fma_f32 v3, -v18, v182, v3
	v_fma_f32 v3, -v19, v183, v3
	s_waitcnt lgkmcnt(3)
	v_fma_f32 v3, -v16, v184, v3
	v_fma_f32 v3, -v17, v185, v3
	v_fma_f32 v3, -v14, v186, v3
	v_fma_f32 v3, -v15, v187, v3
	s_waitcnt lgkmcnt(2)
	v_fma_f32 v3, -v12, v188, v3
	v_fma_f32 v3, -v13, v189, v3
	v_fma_f32 v3, -v10, v190, v3
	v_fma_f32 v3, -v11, v191, v3
	s_waitcnt lgkmcnt(1)
	v_fma_f32 v3, -v8, v192, v3
	v_fma_f32 v3, -v9, v193, v3
	v_fma_f32 v3, -v6, v194, v3
	v_fma_f32 v3, -v7, v195, v3
	s_waitcnt lgkmcnt(0)
	v_fma_f32 v3, -v4, v196, v3
	v_fma_f32 v3, -v197, v5, v3
	v_fma_f32 v3, -v198, v2, v3
	s_cbranch_vccnz .LBB0_828
; __device__ __forceinline__ unsigned short f2bf(float f) { return (unsigned short)(pg8::cvt_pk_bf16(f, 0.f) & 0xffffu); }
; __device__ __forceinline__ void dn_prep_item(int item, unsigned char* ws, LAS unsigned char* lds, int tid, int lane, int wave) {
;     ...
;         if (half == 0) {
; #pragma unroll
;             for (int i = 0; i < 64; ++i) UUo[(tok0 + i) * 256 + hd * 64 + col] = f2bf(x[i]);
;         } else {
; #pragma unroll
;             for (int i = 0; i < 64; ++i) WW[(tok0 + i) * 256 + hd * 64 + col] = f2bf(x[i]);
;         }
	v_readlane_b32 s0, v250, 7
	v_readlane_b32 s1, v250, 8
	s_add_u32 s0, s0, s40
	s_addc_u32 s1, s1, s41
	v_lshl_add_u64 v[66:67], s[0:1], 0, v[0:1]
	v_cvt_pk_bf16_f32 v57, v127, v1
	v_lshl_add_u64 v[66:67], v[66:67], 0, s[18:19]
	global_store_short v[66:67], v57, off
	v_cvt_pk_bf16_f32 v57, v26, v1
	global_store_short v[66:67], v57, off offset:512
	v_cvt_pk_bf16_f32 v57, v27, v1
	global_store_short v[66:67], v57, off offset:1024
	v_cvt_pk_bf16_f32 v57, v30, v1
	global_store_short v[66:67], v57, off offset:1536
	v_cvt_pk_bf16_f32 v57, v31, v1
	global_store_short v[66:67], v57, off offset:2048
	v_cvt_pk_bf16_f32 v57, v32, v1
	v_add_co_u32_e32 v68, vcc, s37, v66
	global_store_short v[66:67], v57, off offset:2560
	v_cvt_pk_bf16_f32 v57, v33, v1
	s_nop 0
	v_addc_co_u32_e32 v69, vcc, 0, v67, vcc
	global_store_short v[66:67], v57, off offset:3072
	v_cvt_pk_bf16_f32 v57, v36, v1
	v_add_co_u32_e32 v70, vcc, s77, v66
	global_store_short v[66:67], v57, off offset:3584
	v_cvt_pk_bf16_f32 v57, v37, v1
	s_nop 0
	v_addc_co_u32_e32 v71, vcc, 0, v67, vcc
	global_store_short v[70:71], v57, off offset:-4096
	v_cvt_pk_bf16_f32 v57, v38, v1
	global_store_short v[68:69], v57, off offset:512
	v_cvt_pk_bf16_f32 v57, v39, v1
	global_store_short v[68:69], v57, off offset:1024
	v_cvt_pk_bf16_f32 v57, v40, v1
	global_store_short v[68:69], v57, off offset:1536
	v_cvt_pk_bf16_f32 v57, v41, v1
	global_store_short v[68:69], v57, off offset:2048
	v_cvt_pk_bf16_f32 v57, v42, v1
	global_store_short v[68:69], v57, off offset:2560
	v_cvt_pk_bf16_f32 v57, v43, v1
	global_store_short v[68:69], v57, off offset:3072
	v_cvt_pk_bf16_f32 v57, v44, v1
	global_store_short v[68:69], v57, off offset:3584
	v_cvt_pk_bf16_f32 v57, v45, v1
	global_store_short v[70:71], v57, off
	v_cvt_pk_bf16_f32 v57, v46, v1
	global_store_short v[70:71], v57, off offset:512
	v_cvt_pk_bf16_f32 v57, v47, v1
	global_store_short v[70:71], v57, off offset:1024
	v_cvt_pk_bf16_f32 v57, v50, v1
	global_store_short v[70:71], v57, off offset:1536
	v_cvt_pk_bf16_f32 v57, v51, v1
	s_movk_i32 s0, 0x3000
	global_store_short v[70:71], v57, off offset:2048
	v_cvt_pk_bf16_f32 v57, v52, v1
	v_add_co_u32_e32 v68, vcc, s0, v66
	global_store_short v[70:71], v57, off offset:2560
	v_cvt_pk_bf16_f32 v57, v53, v1
	s_nop 0
	v_addc_co_u32_e32 v69, vcc, 0, v67, vcc
	s_movk_i32 s0, 0x4000
	global_store_short v[70:71], v57, off offset:3072
	v_cvt_pk_bf16_f32 v57, v56, v1
	global_store_short v[70:71], v57, off offset:3584
	v_add_co_u32_e32 v70, vcc, s0, v66
	v_cvt_pk_bf16_f32 v57, v58, v1
	s_movk_i32 s0, 0x5000
	s_nop 0
	v_addc_co_u32_e32 v71, vcc, 0, v67, vcc
	global_store_short v[70:71], v57, off offset:-4096
	v_cvt_pk_bf16_f32 v57, v59, v1
	global_store_short v[68:69], v57, off offset:512
	v_cvt_pk_bf16_f32 v57, v60, v1
	global_store_short v[68:69], v57, off offset:1024
	v_cvt_pk_bf16_f32 v57, v61, v1
	global_store_short v[68:69], v57, off offset:1536
	v_cvt_pk_bf16_f32 v57, v62, v1
	global_store_short v[68:69], v57, off offset:2048
	v_cvt_pk_bf16_f32 v57, v63, v1
	global_store_short v[68:69], v57, off offset:2560
	v_cvt_pk_bf16_f32 v57, v64, v1
	global_store_short v[68:69], v57, off offset:3072
	v_cvt_pk_bf16_f32 v57, v65, v1
	global_store_short v[68:69], v57, off offset:3584
	v_cvt_pk_bf16_f32 v57, v54, v1
	global_store_short v[70:71], v57, off
	v_cvt_pk_bf16_f32 v57, v55, v1
	global_store_short v[70:71], v57, off offset:512
	v_cvt_pk_bf16_f32 v57, v34, v1
	global_store_short v[70:71], v57, off offset:1024
	v_cvt_pk_bf16_f32 v57, v35, v1
	global_store_short v[70:71], v57, off offset:1536
	v_cvt_pk_bf16_f32 v57, v48, v1
	global_store_short v[70:71], v57, off offset:2048
	v_cvt_pk_bf16_f32 v57, v49, v1
	v_add_co_u32_e32 v68, vcc, s0, v66
	global_store_short v[70:71], v57, off offset:2560
	v_cvt_pk_bf16_f32 v57, v28, v1
	s_nop 0
	v_addc_co_u32_e32 v69, vcc, 0, v67, vcc
	s_movk_i32 s0, 0x6000
	global_store_short v[70:71], v57, off offset:3072
	v_cvt_pk_bf16_f32 v57, v29, v1
	global_store_short v[70:71], v57, off offset:3584
	v_add_co_u32_e32 v70, vcc, s0, v66
	v_cvt_pk_bf16_f32 v57, v24, v1
	s_movk_i32 s0, 0x7000
	s_nop 0
	v_addc_co_u32_e32 v71, vcc, 0, v67, vcc
	global_store_short v[70:71], v57, off offset:-4096
	v_cvt_pk_bf16_f32 v57, v25, v1
	global_store_short v[68:69], v57, off offset:512
	v_cvt_pk_bf16_f32 v57, v20, v1
	global_store_short v[68:69], v57, off offset:1024
	v_cvt_pk_bf16_f32 v57, v21, v1
	global_store_short v[68:69], v57, off offset:1536
	v_cvt_pk_bf16_f32 v57, v22, v1
	global_store_short v[68:69], v57, off offset:2048
	v_cvt_pk_bf16_f32 v57, v23, v1
	global_store_short v[68:69], v57, off offset:2560
	v_cvt_pk_bf16_f32 v57, v18, v1
	global_store_short v[68:69], v57, off offset:3072
	v_cvt_pk_bf16_f32 v57, v19, v1
	global_store_short v[68:69], v57, off offset:3584
	v_cvt_pk_bf16_f32 v57, v16, v1
	global_store_short v[70:71], v57, off
	v_cvt_pk_bf16_f32 v57, v17, v1
	global_store_short v[70:71], v57, off offset:512
	v_cvt_pk_bf16_f32 v57, v14, v1
	global_store_short v[70:71], v57, off offset:1024
	v_cvt_pk_bf16_f32 v57, v15, v1
	global_store_short v[70:71], v57, off offset:1536
	v_cvt_pk_bf16_f32 v57, v12, v1
	global_store_short v[70:71], v57, off offset:2048
	v_cvt_pk_bf16_f32 v57, v13, v1
	global_store_short v[70:71], v57, off offset:2560
	v_cvt_pk_bf16_f32 v57, v10, v1
	global_store_short v[70:71], v57, off offset:3072
	v_cvt_pk_bf16_f32 v57, v11, v1
	v_add_co_u32_e32 v66, vcc, s0, v66
	global_store_short v[70:71], v57, off offset:3584
	v_cvt_pk_bf16_f32 v57, v8, v1
	s_nop 0
	v_addc_co_u32_e32 v67, vcc, 0, v67, vcc
	global_store_short v[66:67], v57, off
	v_cvt_pk_bf16_f32 v57, v9, v1
	global_store_short v[66:67], v57, off offset:512
	v_cvt_pk_bf16_f32 v57, v6, v1
	global_store_short v[66:67], v57, off offset:1024
	v_cvt_pk_bf16_f32 v57, v7, v1
	global_store_short v[66:67], v57, off offset:1536
	v_cvt_pk_bf16_f32 v57, v4, v1
	global_store_short v[66:67], v57, off offset:2048
	v_cvt_pk_bf16_f32 v57, v5, v1
	global_store_short v[66:67], v57, off offset:2560
	v_cvt_pk_bf16_f32 v57, v2, v1
	s_mov_b64 s[10:11], 0
	global_store_short v[66:67], v57, off offset:3072
	v_cvt_pk_bf16_f32 v57, v3, v1
